# phase 5: last 512 token rows as 128 tiles of 64x64 with a 4-stage LDS-DMA ring (main loop = 2 tiles per workgroup); grid barriers: the 41st arriver on an XCD starts an early L2 write-back
# speedup vs baseline: 1.0414x; 1.0083x over previous
; DI unsigned xb_ld(unsigned* p) { return __hip_atomic_load(p, __ATOMIC_RELAXED, __HIP_MEMORY_SCOPE_AGENT); }
; DI unsigned xb_add(unsigned* p, unsigned v) { return __hip_atomic_fetch_add(p, v, __ATOMIC_RELAXED, __HIP_MEMORY_SCOPE_AGENT); }
; #define XB_SPIN(cond, bar) do { unsigned _sp = 0; while (cond) { __builtin_amdgcn_s_sleep(2); \
;     if ((++_sp & 255u) == 0u) { if (xb_ld(&(bar)[XB_TMO])) break; if (_sp > XB_SPIN_CAP) { atomicAdd(&(bar)[XB_TMO], 1u); break; } } } } while (0)
; DI void xcd_barrier(const XcdBarrier& b) {
;     ...
;     if (threadIdx.x == 0) {
;         unsigned* bar = b.bar;
;         __builtin_amdgcn_s_waitcnt(0);
;         unsigned nloc = b.st[0], nx = b.st[1];
;         if (nloc == 0u) { xcd_barrier_complete(bar, b.x, nloc, nx); b.st[0] = nloc; b.st[1] = nx; }
;         const unsigned old = xb_add(&bar[XB_XSUB(b.x)], 1u);
;         const unsigned gen = old / nloc;
;         if (old + 1u == (gen + 1u) * nloc) {
;             __builtin_amdgcn_fence(__ATOMIC_RELEASE, "agent");
;             asm volatile("s_waitcnt vmcnt(0)" ::: "memory");
;             const unsigned og = xb_add(&bar[XB_TOP], 1u);
;             const unsigned tg = og / nx;
;             if (og + 1u == (tg + 1u) * nx) xb_add(&bar[XB_TOPGEN], 1u);
;             else XB_SPIN(xb_ld(&bar[XB_TOPGEN]) == tg, bar);
;             __builtin_amdgcn_fence(__ATOMIC_ACQUIRE, "agent");
;             xb_add(&bar[XB_XGEN(b.x)], 1u);
;             asm volatile("s_waitcnt vmcnt(0)" ::: "memory");
;         } else {
;             XB_SPIN(xb_ld(&bar[XB_XGEN(b.x)]) == gen, bar);
.LBB0_60:
	s_or_b64 exec, exec, s[10:11]
	v_cvt_f32_u32_e32 v6, v4
	s_waitcnt vmcnt(0)
	v_readfirstlane_b32 s6, v5
	s_and_b32 s96, s6, 63
	s_cmp_lg_u32 s96, 40
	s_cbranch_scc1 .Lbw_0_0
	buffer_wbl2 sc1
.Lbw_0_0:
	v_sub_u32_e32 v5, 0, v4
	v_rcp_iflag_f32_e32 v6, v6
	v_add_u32_e32 v7, s6, v3
	v_mul_f32_e32 v6, 0x4f7ffffe, v6
	v_cvt_u32_f32_e32 v6, v6
	v_mul_lo_u32 v3, v5, v6
	v_mul_hi_u32 v3, v6, v3
	v_add_u32_e32 v3, v6, v3
	v_mul_hi_u32 v3, v7, v3
	v_mul_lo_u32 v5, v3, v4
	v_sub_u32_e32 v5, v7, v5
	v_add_u32_e32 v6, 1, v3
	v_cmp_ge_u32_e32 vcc, v5, v4
	s_nop 1
	v_cndmask_b32_e32 v3, v3, v6, vcc
	v_sub_u32_e32 v6, v5, v4
	v_cndmask_b32_e32 v5, v5, v6, vcc
	v_add_u32_e32 v6, 1, v3
	v_cmp_ge_u32_e32 vcc, v5, v4
	v_add_u32_e32 v5, 1, v7
	s_nop 0
	v_cndmask_b32_e32 v3, v3, v6, vcc
	v_mul_lo_u32 v6, v4, v3
	v_add_u32_e32 v4, v6, v4
	v_cmp_ne_u32_e32 vcc, v5, v4
	s_and_saveexec_b64 s[6:7], vcc
	s_xor_b64 s[10:11], exec, s[6:7]
	s_cbranch_execz .LBB0_74
	s_waitcnt lgkmcnt(0)
	v_mov_b32_e32 v2, 0x2000
	global_load_dword v2, v2, s[8:9] offset:1024 sc1
	s_add_u32 s16, s8, 0x2400
	s_addc_u32 s17, s9, 0
	s_waitcnt vmcnt(0)
	v_cmp_eq_u32_e32 vcc, v2, v3
	s_and_saveexec_b64 s[12:13], vcc
	s_cbranch_execz .LBB0_73
	s_add_u32 s14, s54, 0xfc14a00
	s_addc_u32 s15, s55, 0
	s_mov_b32 s6, 1
	s_mov_b64 s[18:19], 0
	v_mov_b32_e32 v2, 0
	s_branch .LBB0_64

; DI unsigned xb_ld(unsigned* p) { return __hip_atomic_load(p, __ATOMIC_RELAXED, __HIP_MEMORY_SCOPE_AGENT); }
; DI unsigned xb_add(unsigned* p, unsigned v) { return __hip_atomic_fetch_add(p, v, __ATOMIC_RELAXED, __HIP_MEMORY_SCOPE_AGENT); }
; #define XB_SPIN(cond, bar) do { unsigned _sp = 0; while (cond) { __builtin_amdgcn_s_sleep(2); \
;     if ((++_sp & 255u) == 0u) { if (xb_ld(&(bar)[XB_TMO])) break; if (_sp > XB_SPIN_CAP) { atomicAdd(&(bar)[XB_TMO], 1u); break; } } } } while (0)
; DI void xcd_barrier(const XcdBarrier& b) {
;     ...
;     if (threadIdx.x == 0) {
;         unsigned* bar = b.bar;
;         __builtin_amdgcn_s_waitcnt(0);
;         unsigned nloc = b.st[0], nx = b.st[1];
;         if (nloc == 0u) { xcd_barrier_complete(bar, b.x, nloc, nx); b.st[0] = nloc; b.st[1] = nx; }
;         const unsigned old = xb_add(&bar[XB_XSUB(b.x)], 1u);
;         const unsigned gen = old / nloc;
;         if (old + 1u == (gen + 1u) * nloc) {
;             __builtin_amdgcn_fence(__ATOMIC_RELEASE, "agent");
;             asm volatile("s_waitcnt vmcnt(0)" ::: "memory");
;             const unsigned og = xb_add(&bar[XB_TOP], 1u);
;             const unsigned tg = og / nx;
;             if (og + 1u == (tg + 1u) * nx) xb_add(&bar[XB_TOPGEN], 1u);
;             else XB_SPIN(xb_ld(&bar[XB_TOPGEN]) == tg, bar);
;             __builtin_amdgcn_fence(__ATOMIC_ACQUIRE, "agent");
;             xb_add(&bar[XB_XGEN(b.x)], 1u);
;             asm volatile("s_waitcnt vmcnt(0)" ::: "memory");
;         } else {
;             XB_SPIN(xb_ld(&bar[XB_XGEN(b.x)]) == gen, bar);
.LBB0_162:
	s_or_b64 exec, exec, s[6:7]
	v_cvt_f32_u32_e32 v6, v4
	s_waitcnt vmcnt(0)
	v_readfirstlane_b32 s2, v5
	s_and_b32 s96, s2, 63
	s_cmp_lg_u32 s96, 40
	s_cbranch_scc1 .Lbw_1_0
	buffer_wbl2 sc1
.Lbw_1_0:
	v_sub_u32_e32 v5, 0, v4
	v_rcp_iflag_f32_e32 v6, v6
	v_add_u32_e32 v7, s2, v3
	v_mul_f32_e32 v6, 0x4f7ffffe, v6
	v_cvt_u32_f32_e32 v6, v6
	v_mul_lo_u32 v3, v5, v6
	v_mul_hi_u32 v3, v6, v3
	v_add_u32_e32 v3, v6, v3
	v_mul_hi_u32 v3, v7, v3
	v_mul_lo_u32 v5, v3, v4
	v_sub_u32_e32 v5, v7, v5
	v_add_u32_e32 v6, 1, v3
	v_cmp_ge_u32_e32 vcc, v5, v4
	s_nop 1
	v_cndmask_b32_e32 v3, v3, v6, vcc
	v_sub_u32_e32 v6, v5, v4
	v_cndmask_b32_e32 v5, v5, v6, vcc
	v_add_u32_e32 v6, 1, v3
	v_cmp_ge_u32_e32 vcc, v5, v4
	v_add_u32_e32 v5, 1, v7
	s_nop 0
	v_cndmask_b32_e32 v3, v3, v6, vcc
	v_mul_lo_u32 v6, v4, v3
	v_add_u32_e32 v4, v6, v4
	v_cmp_ne_u32_e32 vcc, v5, v4
	s_and_saveexec_b64 s[2:3], vcc
	s_xor_b64 s[6:7], exec, s[2:3]
	s_cbranch_execz .LBB0_176
	s_waitcnt lgkmcnt(0)
	v_mov_b32_e32 v2, 0x2000
	global_load_dword v2, v2, s[4:5] offset:1024 sc1
	s_add_u32 s12, s4, 0x2400
	s_addc_u32 s13, s5, 0
	s_waitcnt vmcnt(0)
	v_cmp_eq_u32_e32 vcc, v2, v3
	s_and_saveexec_b64 s[8:9], vcc
	s_cbranch_execz .LBB0_175
	s_add_u32 s10, s54, 0xfc14a00
	s_addc_u32 s11, s55, 0
	s_mov_b32 s2, 1
	s_mov_b64 s[14:15], 0
	v_mov_b32_e32 v2, 0
	s_branch .LBB0_166

; DI unsigned xb_ld(unsigned* p) { return __hip_atomic_load(p, __ATOMIC_RELAXED, __HIP_MEMORY_SCOPE_AGENT); }
; DI unsigned xb_add(unsigned* p, unsigned v) { return __hip_atomic_fetch_add(p, v, __ATOMIC_RELAXED, __HIP_MEMORY_SCOPE_AGENT); }
; #define XB_SPIN(cond, bar) do { unsigned _sp = 0; while (cond) { __builtin_amdgcn_s_sleep(2); \
;     if ((++_sp & 255u) == 0u) { if (xb_ld(&(bar)[XB_TMO])) break; if (_sp > XB_SPIN_CAP) { atomicAdd(&(bar)[XB_TMO], 1u); break; } } } } while (0)
; DI void xcd_barrier(const XcdBarrier& b) {
;     ...
;     if (threadIdx.x == 0) {
;         unsigned* bar = b.bar;
;         __builtin_amdgcn_s_waitcnt(0);
;         unsigned nloc = b.st[0], nx = b.st[1];
;         if (nloc == 0u) { xcd_barrier_complete(bar, b.x, nloc, nx); b.st[0] = nloc; b.st[1] = nx; }
;         const unsigned old = xb_add(&bar[XB_XSUB(b.x)], 1u);
;         const unsigned gen = old / nloc;
;         if (old + 1u == (gen + 1u) * nloc) {
;             __builtin_amdgcn_fence(__ATOMIC_RELEASE, "agent");
;             asm volatile("s_waitcnt vmcnt(0)" ::: "memory");
;             const unsigned og = xb_add(&bar[XB_TOP], 1u);
;             const unsigned tg = og / nx;
;             if (og + 1u == (tg + 1u) * nx) xb_add(&bar[XB_TOPGEN], 1u);
;             else XB_SPIN(xb_ld(&bar[XB_TOPGEN]) == tg, bar);
;             __builtin_amdgcn_fence(__ATOMIC_ACQUIRE, "agent");
;             xb_add(&bar[XB_XGEN(b.x)], 1u);
;             asm volatile("s_waitcnt vmcnt(0)" ::: "memory");
;         } else {
;             XB_SPIN(xb_ld(&bar[XB_XGEN(b.x)]) == gen, bar);
.LBB0_541:
	s_or_b64 exec, exec, s[6:7]
	v_cvt_f32_u32_e32 v5, v3
	s_waitcnt vmcnt(0)
	v_readfirstlane_b32 s4, v4
	s_and_b32 s96, s4, 63
	s_cmp_lg_u32 s96, 40
	s_cbranch_scc1 .Lbw_4_0
	buffer_wbl2 sc1
.Lbw_4_0:
	v_sub_u32_e32 v4, 0, v3
	v_rcp_iflag_f32_e32 v5, v5
	v_add_u32_e32 v6, s4, v2
	v_mul_f32_e32 v5, 0x4f7ffffe, v5
	v_cvt_u32_f32_e32 v5, v5
	v_mul_lo_u32 v2, v4, v5
	v_mul_hi_u32 v2, v5, v2
	v_add_u32_e32 v2, v5, v2
	v_mul_hi_u32 v2, v6, v2
	v_mul_lo_u32 v4, v2, v3
	v_sub_u32_e32 v4, v6, v4
	v_add_u32_e32 v5, 1, v2
	v_cmp_ge_u32_e32 vcc, v4, v3
	s_nop 1
	v_cndmask_b32_e32 v2, v2, v5, vcc
	v_sub_u32_e32 v5, v4, v3
	v_cndmask_b32_e32 v4, v4, v5, vcc
	v_add_u32_e32 v5, 1, v2
	v_cmp_ge_u32_e32 vcc, v4, v3
	v_add_u32_e32 v4, 1, v6
	s_nop 0
	v_cndmask_b32_e32 v2, v2, v5, vcc
	v_mul_lo_u32 v5, v3, v2
	v_add_u32_e32 v3, v5, v3
	v_cmp_ne_u32_e32 vcc, v4, v3
	s_and_saveexec_b64 s[4:5], vcc
	s_xor_b64 s[4:5], exec, s[4:5]
	s_cbranch_execz .LBB0_555
	s_waitcnt lgkmcnt(0)
	v_mov_b32_e32 v1, 0x2000
	global_load_dword v1, v1, s[2:3] offset:1024 sc1
	s_add_u32 s10, s2, 0x2400
	s_addc_u32 s11, s3, 0
	s_waitcnt vmcnt(0)
	v_cmp_eq_u32_e32 vcc, v1, v2
	s_and_saveexec_b64 s[6:7], vcc
	s_cbranch_execz .LBB0_554
	s_add_u32 s8, s54, 0xfc14a00
	s_addc_u32 s9, s55, 0
	s_mov_b32 s22, 1
	s_mov_b64 s[12:13], 0
	v_mov_b32_e32 v1, 0
	s_branch .LBB0_545

; DI void gemm_out(const Params& p, char* lds) {
;     const u16* __restrict__ A = (const u16*)(p.ws + W_XB); const u16* __restrict__ B = (const u16*)(p.ws + W_WOUTT);
;     const int ntile = 176 * 8;
;     const int vb = (blockIdx.x & 7) * (gridDim.x >> 3) + (blockIdx.x >> 3);
;     for (int tile = vb; tile < ntile; tile += gridDim.x) {
;         int tid = threadIdx.x; asm volatile("" : "+v"(tid));
;         const int lane = tid & 63, wave = __builtin_amdgcn_readfirstlane(tid >> 6); const int wn = wave >> 1, wm = wave & 1; const int q = lane & 15, g = lane >> 4;
;         const int mt = tile >> 3, nt = tile & 7; const int m0 = mt * 96, n0 = nt * 128;
;         f32x4 acc[4][3];
; #pragma unroll
;         for (int a = 0; a < 4; ++a)
; #pragma unroll
;             for (int b = 0; b < 3; ++b) acc[a][b] = (f32x4){0.f, 0.f, 0.f, 0.f};
;         unsigned soffb[4], soffa[3];
; #pragma unroll
;         for (int i = 0; i < 4; ++i) { const int row = 8 * (i * 4 + wave) + (lane >> 3); const int ch = (lane & 7) ^ ((row >> 1) & 7); soffb[i] = (unsigned)(row * 1024 + ch * 8); }
; #pragma unroll
;         for (int i = 0; i < 3; ++i) { const int row = 8 * (i * 4 + wave) + (lane >> 3); const int ch = (lane & 7) ^ ((row >> 1) & 7); soffa[i] = (unsigned)(row * 1024 + ch * 8); }
;         const u16* ga = A + (size_t)m0 * 1024; const u16* gb = B + (size_t)n0 * 1024;
;     ...
;         OSTAGE(0, 0);
.LBB0_575:
	s_or_b64 exec, exec, s[0:1]
	s_cmpk_gt_i32 s64, 0x57f
	s_waitcnt lgkmcnt(0)
	s_barrier
	s_cmpk_gt_i32 s64, 0x41f
	s_cbranch_scc1 .LBB0_578
	s_mov_b32 s33, s64
	v_readlane_b32 s95, v236, 8
	s_add_u32 s10, s54, 0x2940000
	s_addc_u32 s11, s55, 0
	v_writelane_b32 v236, s10, 9
	s_nop 1
	v_writelane_b32 v236, s11, 11
	s_lshr_b32 s82, s33, 3
	s_lshl_b32 s82, s82, 7
	s_and_b32 s0, s33, 7
	s_lshl_b32 s0, s0, 7
	v_mov_b32_e32 v75, 0
	v_readfirstlane_b32 s4, v0
	s_lshr_b32 s6, s4, 6
	v_bfe_u32 v2, v0, 3, 3
	s_ashr_i32 s83, s82, 31
	v_lshl_or_b32 v2, s6, 3, v2
	s_lshl_b64 s[4:5], s[82:83], 11
	v_lshrrev_b32_e32 v3, 1, v2
	s_add_u32 s4, s54, s4
	v_xor_b32_e32 v3, v3, v0
	s_addc_u32 s5, s55, s5
	s_ashr_i32 s1, s0, 31
	s_lshl_b32 s8, s6, 10
	s_lshl_b64 s[6:7], s[0:1], 11
	v_lshlrev_b32_e32 v3, 4, v3
	s_add_u32 s6, s10, s6
	v_and_b32_e32 v3, 0x70, v3
	v_add_u32_e32 v4, 32, v2
	s_addc_u32 s7, s11, s7
	v_lshl_or_b32 v74, v2, 11, v3
	s_add_i32 s1, s8, 0
	v_lshrrev_b32_e32 v5, 1, v4
	v_add_u32_e32 v6, 64, v2
	v_add_u32_e32 v8, 0x60, v2
	v_lshl_add_u64 v[2:3], s[4:5], 0, v[74:75]
	s_mov_b32 m0, s1
	v_xor_b32_e32 v5, v5, v0
	global_load_lds_dwordx4 v[2:3], off
	v_lshl_add_u64 v[2:3], s[6:7], 0, v[74:75]
	s_add_i32 m0, s1, 0x4000
	v_lshrrev_b32_e32 v7, 1, v6
	global_load_lds_dwordx4 v[2:3], off
	v_lshlrev_b32_e32 v2, 4, v5
	v_and_b32_e32 v2, 0x70, v2
	v_lshl_or_b32 v74, v4, 11, v2
	v_lshl_add_u64 v[2:3], s[4:5], 0, v[74:75]
	s_add_i32 m0, s1, 0x1000
	v_xor_b32_e32 v7, v7, v0
	global_load_lds_dwordx4 v[2:3], off
	v_lshl_add_u64 v[2:3], s[6:7], 0, v[74:75]
	s_add_i32 m0, s1, 0x5000
	v_lshrrev_b32_e32 v9, 1, v8
	global_load_lds_dwordx4 v[2:3], off
	v_lshlrev_b32_e32 v2, 4, v7
	v_and_b32_e32 v2, 0x70, v2
	v_lshl_or_b32 v74, v6, 11, v2
	v_lshl_add_u64 v[2:3], s[4:5], 0, v[74:75]
	s_add_i32 m0, s1, 0x2000
	v_xor_b32_e32 v9, v9, v0
	global_load_lds_dwordx4 v[2:3], off
	v_lshl_add_u64 v[2:3], s[6:7], 0, v[74:75]
	s_add_i32 m0, s1, 0x6000
	global_load_lds_dwordx4 v[2:3], off
	v_lshlrev_b32_e32 v2, 4, v9
	v_and_b32_e32 v2, 0x70, v2
	v_lshl_or_b32 v74, v8, 11, v2
	v_lshl_add_u64 v[2:3], s[4:5], 0, v[74:75]
	s_add_i32 m0, s1, 0x3000
	global_load_lds_dwordx4 v[2:3], off
	v_lshl_add_u64 v[2:3], s[6:7], 0, v[74:75]
	s_add_i32 m0, s1, 0x7000
	global_load_lds_dwordx4 v[2:3], off
	s_mov_b32 s5, 0
	s_mov_b64 s[8:9], 0x80
	s_mov_b64 s[10:11], 0x100
	s_mov_b64 s[12:13], 0x180
	s_mov_b64 s[14:15], 0x200
	s_mov_b64 s[16:17], 0x280
	s_mov_b64 s[18:19], 0x300
	s_mov_b64 s[20:21], 0x380
	s_mov_b64 s[22:23], 0x400
	s_mov_b64 s[24:25], 0x480
	s_mov_b64 s[26:27], 0x500
	s_mov_b64 s[28:29], 0x580
	s_mov_b64 s[30:31], 0x600
	s_mov_b64 s[36:37], 0x680
	s_mov_b64 s[68:69], 0x700
	s_mov_b64 s[70:71], 0x780
	s_waitcnt vmcnt(0)
.Lo_tile:
	v_mov_b32_e32 v18, v0
	s_ashr_i32 s83, s82, 31
	v_readfirstlane_b32 s1, v18
	s_ashr_i32 s7, s1, 6
	s_ashr_i32 s4, s1, 7
	s_and_b32 s6, s7, 1
	v_bfe_u32 v2, v18, 3, 3
	s_lshl_b64 s[38:39], s[82:83], 11
	v_lshl_or_b32 v2, s7, 3, v2
	s_add_u32 s38, s54, s38
	v_lshrrev_b32_e32 v3, 1, v2
	s_addc_u32 s39, s55, s39
	s_ashr_i32 s1, s0, 31
	v_xor_b32_e32 v3, v3, v18
	s_lshl_b64 s[50:51], s[0:1], 11
	v_readlane_b32 s1, v236, 9
	v_lshlrev_b32_e32 v2, 10, v2
	v_lshlrev_b32_e32 v3, 3, v3
	s_add_u32 s50, s1, s50
	v_readlane_b32 s1, v236, 11
	v_and_or_b32 v74, v3, 56, v2
	s_addc_u32 s51, s1, s51
	s_lshl_b32 s1, s7, 10
	v_lshlrev_b64 v[66:67], 1, v[74:75]
	s_add_i32 s1, s1, 0
	v_add_u32_e32 v2, 0x8000, v74
	v_bfe_u32 v93, v18, 5, 1
	v_lshrrev_b32_e32 v8, 1, v18
	v_mov_b32_e32 v3, v75
	v_lshl_add_u64 v[76:77], s[38:39], 0, v[66:67]
	s_add_i32 s86, s1, 0x8000
	v_bitop3_b32 v10, v93, v8, 7 bitop3:0x78
	v_lshl_add_u64 v[8:9], v[76:77], 0, s[8:9]
	s_mov_b32 m0, s86
	v_lshl_add_u64 v[78:79], s[50:51], 0, v[66:67]
	s_add_i32 s87, s1, 0xc000
	v_lshlrev_b64 v[68:69], 1, v[2:3]
	v_add_u32_e32 v4, 0x10000, v74
	s_waitcnt vmcnt(0) lgkmcnt(0)
	s_barrier
	v_mov_b32_e32 v5, v75
	global_load_lds_dwordx4 v[8:9], off
	v_lshl_add_u64 v[8:9], v[78:79], 0, s[8:9]
	s_mov_b32 m0, s87
	v_lshl_add_u64 v[80:81], s[38:39], 0, v[68:69]
	s_add_i32 s88, s1, 0x9000
	global_load_lds_dwordx4 v[8:9], off
	v_lshl_add_u64 v[2:3], v[80:81], 0, s[8:9]
	s_mov_b32 m0, s88
	v_lshl_add_u64 v[82:83], s[50:51], 0, v[68:69]
	s_add_i32 s89, s1, 0xd000
	v_lshlrev_b64 v[70:71], 1, v[4:5]
	v_add_u32_e32 v6, 0x18000, v74
	v_mov_b32_e32 v7, v75
	global_load_lds_dwordx4 v[2:3], off
	v_lshl_add_u64 v[2:3], v[82:83], 0, s[8:9]
	s_mov_b32 m0, s89
	v_lshl_add_u64 v[84:85], s[38:39], 0, v[70:71]
	s_add_i32 s91, s1, 0xa000
	global_load_lds_dwordx4 v[2:3], off
	v_lshl_add_u64 v[2:3], v[84:85], 0, s[8:9]
	s_mov_b32 m0, s91
	v_lshl_add_u64 v[86:87], s[50:51], 0, v[70:71]
	s_add_i32 s92, s1, 0xe000
	v_lshlrev_b64 v[72:73], 1, v[6:7]
	global_load_lds_dwordx4 v[2:3], off
	v_lshl_add_u64 v[2:3], v[86:87], 0, s[8:9]
	s_mov_b32 m0, s92
	v_lshl_add_u64 v[88:89], s[38:39], 0, v[72:73]
	s_add_i32 s93, s1, 0xb000
	v_and_b32_e32 v94, 31, v18
	global_load_lds_dwordx4 v[2:3], off
	v_lshl_add_u64 v[2:3], v[88:89], 0, s[8:9]
	s_mov_b32 m0, s93
	v_lshl_add_u64 v[90:91], s[50:51], 0, v[72:73]
	s_add_i32 s94, s1, 0xf000
	s_lshl_b32 s7, s4, 13
	v_lshlrev_b32_e32 v116, 7, v94
	global_load_lds_dwordx4 v[2:3], off
	v_lshl_add_u64 v[2:3], v[90:91], 0, s[8:9]
	s_mov_b32 m0, s94
	v_lshl_add_u32 v6, v10, 4, 0
	global_load_lds_dwordx4 v[2:3], off
	v_add3_u32 v74, v6, s7, v116
	ds_read_b128 v[2:5], v74 offset:16384
	s_lshl_b32 s38, s6, 13
	v_add3_u32 v96, v6, s38, v116
	v_bfe_u32 v117, v18, 1, 3
	ds_read_b128 v[6:9], v96
	ds_read_b128 v[10:13], v96 offset:4096
	ds_read_b128 v[14:17], v74 offset:20480
	v_bitop3_b32 v18, v93, v117, 2 bitop3:0x36
	v_lshl_add_u32 v18, v18, 4, 0
	v_add3_u32 v95, v18, s7, v116
	ds_read_b128 v[50:53], v95 offset:16384
	s_waitcnt lgkmcnt(0)
; DI void gemm_out(const Params& p, char* lds) {
;     ...
;         for (int kt = 0; kt < 16; ++kt) {
;             if (kt + 1 < 16) OSTAGE((kt + 1) & 1, kt + 1);
;             const char* sb = lds + (kt & 1) * 28672; const char* sa = sb + 16384;
; #pragma unroll
;             for (int ks = 0; ks < 2; ++ks) {
;                 bf16x8 fw[4], fx[3];
; #pragma unroll
;                 for (int ct = 0; ct < 4; ++ct) fw[ct] = *(const bf16x8*)(sb + swz(wn * 64 + ct * 16 + q, 4 * ks + g));
; #pragma unroll
;                 for (int tt = 0; tt < 3; ++tt) fx[tt] = *(const bf16x8*)(sa + swz(wm * 48 + tt * 16 + q, 4 * ks + g));
; #pragma unroll
;                 for (int ct = 0; ct < 4; ++ct)
; #pragma unroll
;                     for (int tt = 0; tt < 3; ++tt) acc[ct][tt] = __builtin_amdgcn_mfma_f32_16x16x32_bf16(fw[ct], fx[tt], acc[ct][tt], 0, 0, 0);
;             }
;             __syncthreads();
;         }
	v_mfma_f32_32x32x16_bf16 v[34:49], v[6:9], v[2:5], 0
	v_add3_u32 v97, v18, s38, v116
	ds_read_b128 v[98:101], v97
	ds_read_b128 v[102:105], v97 offset:4096
	ds_read_b128 v[106:109], v95 offset:20480
	s_mov_b32 m0, s1
	s_add_i32 s39, s1, 0x5000
	s_add_i32 s50, s1, 0x2000
	s_add_i32 s51, s1, 0x6000
	s_add_i32 s83, s1, 0x3000
	v_mfma_f32_32x32x16_bf16 v[18:33], v[10:13], v[2:5], 0
	s_add_i32 s90, s1, 0x7000
	s_add_i32 s33, s33, s95
	s_waitcnt lgkmcnt(0)
	v_mfma_f32_32x32x16_bf16 v[34:49], v[98:101], v[50:53], v[34:49]
	v_mfma_f32_32x32x16_bf16 v[18:33], v[102:105], v[50:53], v[18:33]
	v_mfma_f32_32x32x16_bf16 v[50:65], v[6:9], v[14:17], 0
	v_mfma_f32_32x32x16_bf16 v[2:17], v[10:13], v[14:17], 0
	v_mfma_f32_32x32x16_bf16 v[50:65], v[98:101], v[106:109], v[50:65]
	v_bitop3_b32 v98, v93, v117, 4 bitop3:0x36
	v_lshl_add_u32 v99, v98, 4, 0
	v_add3_u32 v98, v99, s7, v116
	v_add3_u32 v99, v99, s38, v116
	v_mfma_f32_32x32x16_bf16 v[2:17], v[102:105], v[106:109], v[2:17]
	ds_read_b128 v[100:103], v98 offset:16384
	ds_read_b128 v[104:107], v99
	ds_read_b128 v[108:111], v99 offset:4096
	ds_read_b128 v[112:115], v98 offset:20480
	s_waitcnt lgkmcnt(0)
	v_mfma_f32_32x32x16_bf16 v[34:49], v[104:107], v[100:103], v[34:49]
	v_mfma_f32_32x32x16_bf16 v[18:33], v[108:111], v[100:103], v[18:33]
	v_bitop3_b32 v100, v93, v117, 6 bitop3:0x36
	v_lshl_add_u32 v101, v100, 4, 0
	v_add3_u32 v100, v101, s7, v116
	v_add3_u32 v101, v101, s38, v116
	s_add_i32 s7, s1, 0x4000
	s_add_i32 s38, s1, 0x1000
	s_cmpk_gt_i32 s33, 0x3ff
	v_mfma_f32_32x32x16_bf16 v[50:65], v[104:107], v[112:115], v[50:65]
	v_mfma_f32_32x32x16_bf16 v[2:17], v[108:111], v[112:115], v[2:17]
	ds_read_b128 v[238:241], v100 offset:16384
	ds_read_b128 v[242:245], v101
	ds_read_b128 v[246:249], v101 offset:4096
	ds_read_b128 v[250:253], v100 offset:20480
	s_waitcnt vmcnt(0) lgkmcnt(0)
	s_barrier
	ds_read_b128 v[102:105], v74 offset:49152
	ds_read_b128 v[106:109], v96 offset:32768
	ds_read_b128 v[110:113], v96 offset:36864
	ds_read_b128 v[114:117], v74 offset:53248
	v_mfma_f32_32x32x16_bf16 v[34:49], v[242:245], v[238:241], v[34:49]
	v_mfma_f32_32x32x16_bf16 v[18:33], v[246:249], v[238:241], v[18:33]
	v_lshl_add_u64 v[254:255], v[76:77], 0, s[10:11]
	global_load_lds_dwordx4 v[254:255], off
	v_lshl_add_u64 v[254:255], v[78:79], 0, s[10:11]
	s_mov_b32 m0, s7
	s_nop 0
	global_load_lds_dwordx4 v[254:255], off
	v_mfma_f32_32x32x16_bf16 v[50:65], v[242:245], v[250:253], v[50:65]
	v_lshl_add_u64 v[254:255], v[80:81], 0, s[10:11]
	s_mov_b32 m0, s38
	s_nop 0
	global_load_lds_dwordx4 v[254:255], off
	v_mfma_f32_32x32x16_bf16 v[2:17], v[246:249], v[250:253], v[2:17]
	s_waitcnt lgkmcnt(0)
	ds_read_b128 v[238:241], v95 offset:49152
	ds_read_b128 v[242:245], v97 offset:32768
	ds_read_b128 v[246:249], v97 offset:36864
	ds_read_b128 v[250:253], v95 offset:53248
	v_mfma_f32_32x32x16_bf16 v[34:49], v[106:109], v[102:105], v[34:49]
	v_lshl_add_u64 v[254:255], v[82:83], 0, s[10:11]
	s_mov_b32 m0, s39
	s_nop 0
	global_load_lds_dwordx4 v[254:255], off
	v_mfma_f32_32x32x16_bf16 v[18:33], v[110:113], v[102:105], v[18:33]
	v_lshl_add_u64 v[254:255], v[84:85], 0, s[10:11]
	s_mov_b32 m0, s50
	s_nop 0
	global_load_lds_dwordx4 v[254:255], off
	v_mfma_f32_32x32x16_bf16 v[50:65], v[106:109], v[114:117], v[50:65]
	v_mfma_f32_32x32x16_bf16 v[2:17], v[110:113], v[114:117], v[2:17]
	s_waitcnt lgkmcnt(0)
	ds_read_b128 v[102:105], v98 offset:49152
	ds_read_b128 v[106:109], v99 offset:32768
	ds_read_b128 v[110:113], v99 offset:36864
	ds_read_b128 v[114:117], v98 offset:53248
	v_mfma_f32_32x32x16_bf16 v[34:49], v[242:245], v[238:241], v[34:49]
	v_lshl_add_u64 v[254:255], v[86:87], 0, s[10:11]
	s_mov_b32 m0, s51
	s_nop 0
	global_load_lds_dwordx4 v[254:255], off
	v_mfma_f32_32x32x16_bf16 v[18:33], v[246:249], v[238:241], v[18:33]
	v_lshl_add_u64 v[254:255], v[88:89], 0, s[10:11]
	s_mov_b32 m0, s83
	s_nop 0
	global_load_lds_dwordx4 v[254:255], off
	v_mfma_f32_32x32x16_bf16 v[50:65], v[242:245], v[250:253], v[50:65]
	v_mfma_f32_32x32x16_bf16 v[2:17], v[246:249], v[250:253], v[2:17]
	s_waitcnt lgkmcnt(0)
	ds_read_b128 v[238:241], v100 offset:49152
	ds_read_b128 v[242:245], v101 offset:32768
	ds_read_b128 v[246:249], v101 offset:36864
	ds_read_b128 v[250:253], v100 offset:53248
	v_mfma_f32_32x32x16_bf16 v[34:49], v[106:109], v[102:105], v[34:49]
	v_lshl_add_u64 v[254:255], v[90:91], 0, s[10:11]
	s_mov_b32 m0, s90
	s_nop 0
	global_load_lds_dwordx4 v[254:255], off
	v_mfma_f32_32x32x16_bf16 v[18:33], v[110:113], v[102:105], v[18:33]
	v_mfma_f32_32x32x16_bf16 v[50:65], v[106:109], v[114:117], v[50:65]
	v_mfma_f32_32x32x16_bf16 v[2:17], v[110:113], v[114:117], v[2:17]
	s_mov_b32 m0, s86
	s_waitcnt vmcnt(0) lgkmcnt(0)
	s_barrier
; DI void gemm_out(const Params& p, char* lds) {
;     ...
;         for (int kt = 0; kt < 16; ++kt) {
;             if (kt + 1 < 16) OSTAGE((kt + 1) & 1, kt + 1);
;             const char* sb = lds + (kt & 1) * 28672; const char* sa = sb + 16384;
; #pragma unroll
;             for (int ks = 0; ks < 2; ++ks) {
;                 bf16x8 fw[4], fx[3];
; #pragma unroll
;                 for (int ct = 0; ct < 4; ++ct) fw[ct] = *(const bf16x8*)(sb + swz(wn * 64 + ct * 16 + q, 4 * ks + g));
; #pragma unroll
;                 for (int tt = 0; tt < 3; ++tt) fx[tt] = *(const bf16x8*)(sa + swz(wm * 48 + tt * 16 + q, 4 * ks + g));
; #pragma unroll
;                 for (int ct = 0; ct < 4; ++ct)
; #pragma unroll
;                     for (int tt = 0; tt < 3; ++tt) acc[ct][tt] = __builtin_amdgcn_mfma_f32_16x16x32_bf16(fw[ct], fx[tt], acc[ct][tt], 0, 0, 0);
;             }
;             __syncthreads();
;         }
	ds_read_b128 v[102:105], v74 offset:16384
	ds_read_b128 v[106:109], v96
	ds_read_b128 v[110:113], v96 offset:4096
	ds_read_b128 v[114:117], v74 offset:20480
	v_mfma_f32_32x32x16_bf16 v[34:49], v[242:245], v[238:241], v[34:49]
	v_mfma_f32_32x32x16_bf16 v[18:33], v[246:249], v[238:241], v[18:33]
	v_lshl_add_u64 v[254:255], v[76:77], 0, s[12:13]
	global_load_lds_dwordx4 v[254:255], off
	v_lshl_add_u64 v[254:255], v[78:79], 0, s[12:13]
	s_mov_b32 m0, s87
	s_nop 0
	global_load_lds_dwordx4 v[254:255], off
	v_mfma_f32_32x32x16_bf16 v[50:65], v[242:245], v[250:253], v[50:65]
	v_lshl_add_u64 v[254:255], v[80:81], 0, s[12:13]
	s_mov_b32 m0, s88
	s_nop 0
	global_load_lds_dwordx4 v[254:255], off
	v_mfma_f32_32x32x16_bf16 v[2:17], v[246:249], v[250:253], v[2:17]
	s_waitcnt lgkmcnt(0)
	ds_read_b128 v[238:241], v95 offset:16384
	ds_read_b128 v[242:245], v97
	ds_read_b128 v[246:249], v97 offset:4096
	ds_read_b128 v[250:253], v95 offset:20480
	v_mfma_f32_32x32x16_bf16 v[34:49], v[106:109], v[102:105], v[34:49]
	v_lshl_add_u64 v[254:255], v[82:83], 0, s[12:13]
	s_mov_b32 m0, s89
	s_nop 0
	global_load_lds_dwordx4 v[254:255], off
	v_mfma_f32_32x32x16_bf16 v[18:33], v[110:113], v[102:105], v[18:33]
	v_lshl_add_u64 v[254:255], v[84:85], 0, s[12:13]
	s_mov_b32 m0, s91
	s_nop 0
	global_load_lds_dwordx4 v[254:255], off
	v_mfma_f32_32x32x16_bf16 v[50:65], v[106:109], v[114:117], v[50:65]
	v_mfma_f32_32x32x16_bf16 v[2:17], v[110:113], v[114:117], v[2:17]
	s_waitcnt lgkmcnt(0)
	ds_read_b128 v[102:105], v98 offset:16384
	ds_read_b128 v[106:109], v99
	ds_read_b128 v[110:113], v99 offset:4096
	ds_read_b128 v[114:117], v98 offset:20480
	v_mfma_f32_32x32x16_bf16 v[34:49], v[242:245], v[238:241], v[34:49]
	v_lshl_add_u64 v[254:255], v[86:87], 0, s[12:13]
	s_mov_b32 m0, s92
	s_nop 0
	global_load_lds_dwordx4 v[254:255], off
	v_mfma_f32_32x32x16_bf16 v[18:33], v[246:249], v[238:241], v[18:33]
	v_lshl_add_u64 v[254:255], v[88:89], 0, s[12:13]
	s_mov_b32 m0, s93
	s_nop 0
	global_load_lds_dwordx4 v[254:255], off
	v_mfma_f32_32x32x16_bf16 v[50:65], v[242:245], v[250:253], v[50:65]
	v_mfma_f32_32x32x16_bf16 v[2:17], v[246:249], v[250:253], v[2:17]
	s_waitcnt lgkmcnt(0)
	ds_read_b128 v[238:241], v100 offset:16384
	ds_read_b128 v[242:245], v101
	ds_read_b128 v[246:249], v101 offset:4096
	ds_read_b128 v[250:253], v100 offset:20480
	v_mfma_f32_32x32x16_bf16 v[34:49], v[106:109], v[102:105], v[34:49]
	v_lshl_add_u64 v[254:255], v[90:91], 0, s[12:13]
	s_mov_b32 m0, s94
	s_nop 0
	global_load_lds_dwordx4 v[254:255], off
	v_mfma_f32_32x32x16_bf16 v[18:33], v[110:113], v[102:105], v[18:33]
	v_mfma_f32_32x32x16_bf16 v[50:65], v[106:109], v[114:117], v[50:65]
	v_mfma_f32_32x32x16_bf16 v[2:17], v[110:113], v[114:117], v[2:17]
	s_mov_b32 m0, s1
	s_waitcnt vmcnt(0) lgkmcnt(0)
	s_barrier
	ds_read_b128 v[102:105], v74 offset:49152
	ds_read_b128 v[106:109], v96 offset:32768
	ds_read_b128 v[110:113], v96 offset:36864
	ds_read_b128 v[114:117], v74 offset:53248
	v_mfma_f32_32x32x16_bf16 v[34:49], v[242:245], v[238:241], v[34:49]
	v_mfma_f32_32x32x16_bf16 v[18:33], v[246:249], v[238:241], v[18:33]
	v_lshl_add_u64 v[254:255], v[76:77], 0, s[14:15]
	global_load_lds_dwordx4 v[254:255], off
	v_lshl_add_u64 v[254:255], v[78:79], 0, s[14:15]
	s_mov_b32 m0, s7
	s_nop 0
	global_load_lds_dwordx4 v[254:255], off
	v_mfma_f32_32x32x16_bf16 v[50:65], v[242:245], v[250:253], v[50:65]
	v_lshl_add_u64 v[254:255], v[80:81], 0, s[14:15]
	s_mov_b32 m0, s38
	s_nop 0
	global_load_lds_dwordx4 v[254:255], off
	v_mfma_f32_32x32x16_bf16 v[2:17], v[246:249], v[250:253], v[2:17]
	s_waitcnt lgkmcnt(0)
	ds_read_b128 v[238:241], v95 offset:49152
	ds_read_b128 v[242:245], v97 offset:32768
	ds_read_b128 v[246:249], v97 offset:36864
	ds_read_b128 v[250:253], v95 offset:53248
	v_mfma_f32_32x32x16_bf16 v[34:49], v[106:109], v[102:105], v[34:49]
	v_lshl_add_u64 v[254:255], v[82:83], 0, s[14:15]
	s_mov_b32 m0, s39
	s_nop 0
	global_load_lds_dwordx4 v[254:255], off
	v_mfma_f32_32x32x16_bf16 v[18:33], v[110:113], v[102:105], v[18:33]
	v_lshl_add_u64 v[254:255], v[84:85], 0, s[14:15]
	s_mov_b32 m0, s50
	s_nop 0
	global_load_lds_dwordx4 v[254:255], off
	v_mfma_f32_32x32x16_bf16 v[50:65], v[106:109], v[114:117], v[50:65]
	v_mfma_f32_32x32x16_bf16 v[2:17], v[110:113], v[114:117], v[2:17]
	s_waitcnt lgkmcnt(0)
	ds_read_b128 v[102:105], v98 offset:49152
	ds_read_b128 v[106:109], v99 offset:32768
	ds_read_b128 v[110:113], v99 offset:36864
	ds_read_b128 v[114:117], v98 offset:53248
	v_mfma_f32_32x32x16_bf16 v[34:49], v[242:245], v[238:241], v[34:49]
	v_lshl_add_u64 v[254:255], v[86:87], 0, s[14:15]
	s_mov_b32 m0, s51
	s_nop 0
	global_load_lds_dwordx4 v[254:255], off
	v_mfma_f32_32x32x16_bf16 v[18:33], v[246:249], v[238:241], v[18:33]
	v_lshl_add_u64 v[254:255], v[88:89], 0, s[14:15]
	s_mov_b32 m0, s83
	s_nop 0
	global_load_lds_dwordx4 v[254:255], off
	v_mfma_f32_32x32x16_bf16 v[50:65], v[242:245], v[250:253], v[50:65]
	v_mfma_f32_32x32x16_bf16 v[2:17], v[246:249], v[250:253], v[2:17]
	s_waitcnt lgkmcnt(0)
	ds_read_b128 v[238:241], v100 offset:49152
	ds_read_b128 v[242:245], v101 offset:32768
	ds_read_b128 v[246:249], v101 offset:36864
	ds_read_b128 v[250:253], v100 offset:53248
	v_mfma_f32_32x32x16_bf16 v[34:49], v[106:109], v[102:105], v[34:49]
	v_lshl_add_u64 v[254:255], v[90:91], 0, s[14:15]
	s_mov_b32 m0, s90
	s_nop 0
	global_load_lds_dwordx4 v[254:255], off
	v_mfma_f32_32x32x16_bf16 v[18:33], v[110:113], v[102:105], v[18:33]
	v_mfma_f32_32x32x16_bf16 v[50:65], v[106:109], v[114:117], v[50:65]
	v_mfma_f32_32x32x16_bf16 v[2:17], v[110:113], v[114:117], v[2:17]
	s_mov_b32 m0, s86
	s_waitcnt vmcnt(0) lgkmcnt(0)
	s_barrier
; DI void gemm_out(const Params& p, char* lds) {
;     ...
;         for (int kt = 0; kt < 16; ++kt) {
;             if (kt + 1 < 16) OSTAGE((kt + 1) & 1, kt + 1);
;             const char* sb = lds + (kt & 1) * 28672; const char* sa = sb + 16384;
; #pragma unroll
;             for (int ks = 0; ks < 2; ++ks) {
;                 bf16x8 fw[4], fx[3];
; #pragma unroll
;                 for (int ct = 0; ct < 4; ++ct) fw[ct] = *(const bf16x8*)(sb + swz(wn * 64 + ct * 16 + q, 4 * ks + g));
; #pragma unroll
;                 for (int tt = 0; tt < 3; ++tt) fx[tt] = *(const bf16x8*)(sa + swz(wm * 48 + tt * 16 + q, 4 * ks + g));
; #pragma unroll
;                 for (int ct = 0; ct < 4; ++ct)
; #pragma unroll
;                     for (int tt = 0; tt < 3; ++tt) acc[ct][tt] = __builtin_amdgcn_mfma_f32_16x16x32_bf16(fw[ct], fx[tt], acc[ct][tt], 0, 0, 0);
;             }
;             __syncthreads();
;         }
	ds_read_b128 v[102:105], v74 offset:16384
	ds_read_b128 v[106:109], v96
	ds_read_b128 v[110:113], v96 offset:4096
	ds_read_b128 v[114:117], v74 offset:20480
	v_mfma_f32_32x32x16_bf16 v[34:49], v[242:245], v[238:241], v[34:49]
	v_mfma_f32_32x32x16_bf16 v[18:33], v[246:249], v[238:241], v[18:33]
	v_lshl_add_u64 v[254:255], v[76:77], 0, s[16:17]
	global_load_lds_dwordx4 v[254:255], off
	v_lshl_add_u64 v[254:255], v[78:79], 0, s[16:17]
	s_mov_b32 m0, s87
	s_nop 0
	global_load_lds_dwordx4 v[254:255], off
	v_mfma_f32_32x32x16_bf16 v[50:65], v[242:245], v[250:253], v[50:65]
	v_lshl_add_u64 v[254:255], v[80:81], 0, s[16:17]
	s_mov_b32 m0, s88
	s_nop 0
	global_load_lds_dwordx4 v[254:255], off
	v_mfma_f32_32x32x16_bf16 v[2:17], v[246:249], v[250:253], v[2:17]
	s_waitcnt lgkmcnt(0)
	ds_read_b128 v[238:241], v95 offset:16384
	ds_read_b128 v[242:245], v97
	ds_read_b128 v[246:249], v97 offset:4096
	ds_read_b128 v[250:253], v95 offset:20480
	v_mfma_f32_32x32x16_bf16 v[34:49], v[106:109], v[102:105], v[34:49]
	v_lshl_add_u64 v[254:255], v[82:83], 0, s[16:17]
	s_mov_b32 m0, s89
	s_nop 0
	global_load_lds_dwordx4 v[254:255], off
	v_mfma_f32_32x32x16_bf16 v[18:33], v[110:113], v[102:105], v[18:33]
	v_lshl_add_u64 v[254:255], v[84:85], 0, s[16:17]
	s_mov_b32 m0, s91
	s_nop 0
	global_load_lds_dwordx4 v[254:255], off
	v_mfma_f32_32x32x16_bf16 v[50:65], v[106:109], v[114:117], v[50:65]
	v_mfma_f32_32x32x16_bf16 v[2:17], v[110:113], v[114:117], v[2:17]
	s_waitcnt lgkmcnt(0)
	ds_read_b128 v[102:105], v98 offset:16384
	ds_read_b128 v[106:109], v99
	ds_read_b128 v[110:113], v99 offset:4096
	ds_read_b128 v[114:117], v98 offset:20480
	v_mfma_f32_32x32x16_bf16 v[34:49], v[242:245], v[238:241], v[34:49]
	v_lshl_add_u64 v[254:255], v[86:87], 0, s[16:17]
	s_mov_b32 m0, s92
	s_nop 0
	global_load_lds_dwordx4 v[254:255], off
	v_mfma_f32_32x32x16_bf16 v[18:33], v[246:249], v[238:241], v[18:33]
	v_lshl_add_u64 v[254:255], v[88:89], 0, s[16:17]
	s_mov_b32 m0, s93
	s_nop 0
	global_load_lds_dwordx4 v[254:255], off
	v_mfma_f32_32x32x16_bf16 v[50:65], v[242:245], v[250:253], v[50:65]
	v_mfma_f32_32x32x16_bf16 v[2:17], v[246:249], v[250:253], v[2:17]
	s_waitcnt lgkmcnt(0)
	ds_read_b128 v[238:241], v100 offset:16384
	ds_read_b128 v[242:245], v101
	ds_read_b128 v[246:249], v101 offset:4096
	ds_read_b128 v[250:253], v100 offset:20480
	v_mfma_f32_32x32x16_bf16 v[34:49], v[106:109], v[102:105], v[34:49]
	v_lshl_add_u64 v[254:255], v[90:91], 0, s[16:17]
	s_mov_b32 m0, s94
	s_nop 0
	global_load_lds_dwordx4 v[254:255], off
	v_mfma_f32_32x32x16_bf16 v[18:33], v[110:113], v[102:105], v[18:33]
	v_mfma_f32_32x32x16_bf16 v[50:65], v[106:109], v[114:117], v[50:65]
	v_mfma_f32_32x32x16_bf16 v[2:17], v[110:113], v[114:117], v[2:17]
	s_mov_b32 m0, s1
	s_waitcnt vmcnt(0) lgkmcnt(0)
	s_barrier
	ds_read_b128 v[102:105], v74 offset:49152
	ds_read_b128 v[106:109], v96 offset:32768
	ds_read_b128 v[110:113], v96 offset:36864
	ds_read_b128 v[114:117], v74 offset:53248
	v_mfma_f32_32x32x16_bf16 v[34:49], v[242:245], v[238:241], v[34:49]
	v_mfma_f32_32x32x16_bf16 v[18:33], v[246:249], v[238:241], v[18:33]
	v_lshl_add_u64 v[254:255], v[76:77], 0, s[18:19]
	global_load_lds_dwordx4 v[254:255], off
	v_lshl_add_u64 v[254:255], v[78:79], 0, s[18:19]
	s_mov_b32 m0, s7
	s_nop 0
	global_load_lds_dwordx4 v[254:255], off
	v_mfma_f32_32x32x16_bf16 v[50:65], v[242:245], v[250:253], v[50:65]
	v_lshl_add_u64 v[254:255], v[80:81], 0, s[18:19]
	s_mov_b32 m0, s38
	s_nop 0
	global_load_lds_dwordx4 v[254:255], off
	v_mfma_f32_32x32x16_bf16 v[2:17], v[246:249], v[250:253], v[2:17]
	s_waitcnt lgkmcnt(0)
	ds_read_b128 v[238:241], v95 offset:49152
	ds_read_b128 v[242:245], v97 offset:32768
	ds_read_b128 v[246:249], v97 offset:36864
	ds_read_b128 v[250:253], v95 offset:53248
	v_mfma_f32_32x32x16_bf16 v[34:49], v[106:109], v[102:105], v[34:49]
	v_lshl_add_u64 v[254:255], v[82:83], 0, s[18:19]
	s_mov_b32 m0, s39
	s_nop 0
	global_load_lds_dwordx4 v[254:255], off
	v_mfma_f32_32x32x16_bf16 v[18:33], v[110:113], v[102:105], v[18:33]
	v_lshl_add_u64 v[254:255], v[84:85], 0, s[18:19]
	s_mov_b32 m0, s50
	s_nop 0
	global_load_lds_dwordx4 v[254:255], off
	v_mfma_f32_32x32x16_bf16 v[50:65], v[106:109], v[114:117], v[50:65]
	v_mfma_f32_32x32x16_bf16 v[2:17], v[110:113], v[114:117], v[2:17]
	s_waitcnt lgkmcnt(0)
	ds_read_b128 v[102:105], v98 offset:49152
	ds_read_b128 v[106:109], v99 offset:32768
	ds_read_b128 v[110:113], v99 offset:36864
	ds_read_b128 v[114:117], v98 offset:53248
	v_mfma_f32_32x32x16_bf16 v[34:49], v[242:245], v[238:241], v[34:49]
	v_lshl_add_u64 v[254:255], v[86:87], 0, s[18:19]
	s_mov_b32 m0, s51
	s_nop 0
	global_load_lds_dwordx4 v[254:255], off
	v_mfma_f32_32x32x16_bf16 v[18:33], v[246:249], v[238:241], v[18:33]
	v_lshl_add_u64 v[254:255], v[88:89], 0, s[18:19]
	s_mov_b32 m0, s83
	s_nop 0
	global_load_lds_dwordx4 v[254:255], off
	v_mfma_f32_32x32x16_bf16 v[50:65], v[242:245], v[250:253], v[50:65]
	v_mfma_f32_32x32x16_bf16 v[2:17], v[246:249], v[250:253], v[2:17]
	s_waitcnt lgkmcnt(0)
	ds_read_b128 v[238:241], v100 offset:49152
	ds_read_b128 v[242:245], v101 offset:32768
	ds_read_b128 v[246:249], v101 offset:36864
	ds_read_b128 v[250:253], v100 offset:53248
	v_mfma_f32_32x32x16_bf16 v[34:49], v[106:109], v[102:105], v[34:49]
	v_lshl_add_u64 v[254:255], v[90:91], 0, s[18:19]
	s_mov_b32 m0, s90
	s_nop 0
	global_load_lds_dwordx4 v[254:255], off
	v_mfma_f32_32x32x16_bf16 v[18:33], v[110:113], v[102:105], v[18:33]
	v_mfma_f32_32x32x16_bf16 v[50:65], v[106:109], v[114:117], v[50:65]
	v_mfma_f32_32x32x16_bf16 v[2:17], v[110:113], v[114:117], v[2:17]
	s_mov_b32 m0, s86
	s_waitcnt vmcnt(0) lgkmcnt(0)
	s_barrier
; DI void gemm_out(const Params& p, char* lds) {
;     ...
;         for (int kt = 0; kt < 16; ++kt) {
;             if (kt + 1 < 16) OSTAGE((kt + 1) & 1, kt + 1);
;             const char* sb = lds + (kt & 1) * 28672; const char* sa = sb + 16384;
; #pragma unroll
;             for (int ks = 0; ks < 2; ++ks) {
;                 bf16x8 fw[4], fx[3];
; #pragma unroll
;                 for (int ct = 0; ct < 4; ++ct) fw[ct] = *(const bf16x8*)(sb + swz(wn * 64 + ct * 16 + q, 4 * ks + g));
; #pragma unroll
;                 for (int tt = 0; tt < 3; ++tt) fx[tt] = *(const bf16x8*)(sa + swz(wm * 48 + tt * 16 + q, 4 * ks + g));
; #pragma unroll
;                 for (int ct = 0; ct < 4; ++ct)
; #pragma unroll
;                     for (int tt = 0; tt < 3; ++tt) acc[ct][tt] = __builtin_amdgcn_mfma_f32_16x16x32_bf16(fw[ct], fx[tt], acc[ct][tt], 0, 0, 0);
;             }
;             __syncthreads();
;         }
	ds_read_b128 v[102:105], v74 offset:16384
	ds_read_b128 v[106:109], v96
	ds_read_b128 v[110:113], v96 offset:4096
	ds_read_b128 v[114:117], v74 offset:20480
	v_mfma_f32_32x32x16_bf16 v[34:49], v[242:245], v[238:241], v[34:49]
	v_mfma_f32_32x32x16_bf16 v[18:33], v[246:249], v[238:241], v[18:33]
	v_lshl_add_u64 v[254:255], v[76:77], 0, s[20:21]
	global_load_lds_dwordx4 v[254:255], off
	v_lshl_add_u64 v[254:255], v[78:79], 0, s[20:21]
	s_mov_b32 m0, s87
	s_nop 0
	global_load_lds_dwordx4 v[254:255], off
	v_mfma_f32_32x32x16_bf16 v[50:65], v[242:245], v[250:253], v[50:65]
	v_lshl_add_u64 v[254:255], v[80:81], 0, s[20:21]
	s_mov_b32 m0, s88
	s_nop 0
	global_load_lds_dwordx4 v[254:255], off
	v_mfma_f32_32x32x16_bf16 v[2:17], v[246:249], v[250:253], v[2:17]
	s_waitcnt lgkmcnt(0)
	ds_read_b128 v[238:241], v95 offset:16384
	ds_read_b128 v[242:245], v97
	ds_read_b128 v[246:249], v97 offset:4096
	ds_read_b128 v[250:253], v95 offset:20480
	v_mfma_f32_32x32x16_bf16 v[34:49], v[106:109], v[102:105], v[34:49]
	v_lshl_add_u64 v[254:255], v[82:83], 0, s[20:21]
	s_mov_b32 m0, s89
	s_nop 0
	global_load_lds_dwordx4 v[254:255], off
	v_mfma_f32_32x32x16_bf16 v[18:33], v[110:113], v[102:105], v[18:33]
	v_lshl_add_u64 v[254:255], v[84:85], 0, s[20:21]
	s_mov_b32 m0, s91
	s_nop 0
	global_load_lds_dwordx4 v[254:255], off
	v_mfma_f32_32x32x16_bf16 v[50:65], v[106:109], v[114:117], v[50:65]
	v_mfma_f32_32x32x16_bf16 v[2:17], v[110:113], v[114:117], v[2:17]
	s_waitcnt lgkmcnt(0)
	ds_read_b128 v[102:105], v98 offset:16384
	ds_read_b128 v[106:109], v99
	ds_read_b128 v[110:113], v99 offset:4096
	ds_read_b128 v[114:117], v98 offset:20480
	v_mfma_f32_32x32x16_bf16 v[34:49], v[242:245], v[238:241], v[34:49]
	v_lshl_add_u64 v[254:255], v[86:87], 0, s[20:21]
	s_mov_b32 m0, s92
	s_nop 0
	global_load_lds_dwordx4 v[254:255], off
	v_mfma_f32_32x32x16_bf16 v[18:33], v[246:249], v[238:241], v[18:33]
	v_lshl_add_u64 v[254:255], v[88:89], 0, s[20:21]
	s_mov_b32 m0, s93
	s_nop 0
	global_load_lds_dwordx4 v[254:255], off
	v_mfma_f32_32x32x16_bf16 v[50:65], v[242:245], v[250:253], v[50:65]
	v_mfma_f32_32x32x16_bf16 v[2:17], v[246:249], v[250:253], v[2:17]
	s_waitcnt lgkmcnt(0)
	ds_read_b128 v[238:241], v100 offset:16384
	ds_read_b128 v[242:245], v101
	ds_read_b128 v[246:249], v101 offset:4096
	ds_read_b128 v[250:253], v100 offset:20480
	v_mfma_f32_32x32x16_bf16 v[34:49], v[106:109], v[102:105], v[34:49]
	v_lshl_add_u64 v[254:255], v[90:91], 0, s[20:21]
	s_mov_b32 m0, s94
	s_nop 0
	global_load_lds_dwordx4 v[254:255], off
	v_mfma_f32_32x32x16_bf16 v[18:33], v[110:113], v[102:105], v[18:33]
	v_mfma_f32_32x32x16_bf16 v[50:65], v[106:109], v[114:117], v[50:65]
	v_mfma_f32_32x32x16_bf16 v[2:17], v[110:113], v[114:117], v[2:17]
	s_mov_b32 m0, s1
	s_waitcnt vmcnt(0) lgkmcnt(0)
	s_barrier
	ds_read_b128 v[102:105], v74 offset:49152
	ds_read_b128 v[106:109], v96 offset:32768
	ds_read_b128 v[110:113], v96 offset:36864
	ds_read_b128 v[114:117], v74 offset:53248
	v_mfma_f32_32x32x16_bf16 v[34:49], v[242:245], v[238:241], v[34:49]
	v_mfma_f32_32x32x16_bf16 v[18:33], v[246:249], v[238:241], v[18:33]
	v_lshl_add_u64 v[254:255], v[76:77], 0, s[22:23]
	global_load_lds_dwordx4 v[254:255], off
	v_lshl_add_u64 v[254:255], v[78:79], 0, s[22:23]
	s_mov_b32 m0, s7
	s_nop 0
	global_load_lds_dwordx4 v[254:255], off
	v_mfma_f32_32x32x16_bf16 v[50:65], v[242:245], v[250:253], v[50:65]
	v_lshl_add_u64 v[254:255], v[80:81], 0, s[22:23]
	s_mov_b32 m0, s38
	s_nop 0
	global_load_lds_dwordx4 v[254:255], off
	v_mfma_f32_32x32x16_bf16 v[2:17], v[246:249], v[250:253], v[2:17]
	s_waitcnt lgkmcnt(0)
	ds_read_b128 v[238:241], v95 offset:49152
	ds_read_b128 v[242:245], v97 offset:32768
	ds_read_b128 v[246:249], v97 offset:36864
	ds_read_b128 v[250:253], v95 offset:53248
	v_mfma_f32_32x32x16_bf16 v[34:49], v[106:109], v[102:105], v[34:49]
	v_lshl_add_u64 v[254:255], v[82:83], 0, s[22:23]
	s_mov_b32 m0, s39
	s_nop 0
	global_load_lds_dwordx4 v[254:255], off
	v_mfma_f32_32x32x16_bf16 v[18:33], v[110:113], v[102:105], v[18:33]
	v_lshl_add_u64 v[254:255], v[84:85], 0, s[22:23]
	s_mov_b32 m0, s50
	s_nop 0
	global_load_lds_dwordx4 v[254:255], off
	v_mfma_f32_32x32x16_bf16 v[50:65], v[106:109], v[114:117], v[50:65]
	v_mfma_f32_32x32x16_bf16 v[2:17], v[110:113], v[114:117], v[2:17]
	s_waitcnt lgkmcnt(0)
	ds_read_b128 v[102:105], v98 offset:49152
	ds_read_b128 v[106:109], v99 offset:32768
	ds_read_b128 v[110:113], v99 offset:36864
	ds_read_b128 v[114:117], v98 offset:53248
	v_mfma_f32_32x32x16_bf16 v[34:49], v[242:245], v[238:241], v[34:49]
	v_lshl_add_u64 v[254:255], v[86:87], 0, s[22:23]
	s_mov_b32 m0, s51
	s_nop 0
	global_load_lds_dwordx4 v[254:255], off
	v_mfma_f32_32x32x16_bf16 v[18:33], v[246:249], v[238:241], v[18:33]
	v_lshl_add_u64 v[254:255], v[88:89], 0, s[22:23]
	s_mov_b32 m0, s83
	s_nop 0
	global_load_lds_dwordx4 v[254:255], off
	v_mfma_f32_32x32x16_bf16 v[50:65], v[242:245], v[250:253], v[50:65]
	v_mfma_f32_32x32x16_bf16 v[2:17], v[246:249], v[250:253], v[2:17]
	s_waitcnt lgkmcnt(0)
	ds_read_b128 v[238:241], v100 offset:49152
	ds_read_b128 v[242:245], v101 offset:32768
	ds_read_b128 v[246:249], v101 offset:36864
	ds_read_b128 v[250:253], v100 offset:53248
	v_mfma_f32_32x32x16_bf16 v[34:49], v[106:109], v[102:105], v[34:49]
	v_lshl_add_u64 v[254:255], v[90:91], 0, s[22:23]
	s_mov_b32 m0, s90
	s_nop 0
	global_load_lds_dwordx4 v[254:255], off
	v_mfma_f32_32x32x16_bf16 v[18:33], v[110:113], v[102:105], v[18:33]
	v_mfma_f32_32x32x16_bf16 v[50:65], v[106:109], v[114:117], v[50:65]
	v_mfma_f32_32x32x16_bf16 v[2:17], v[110:113], v[114:117], v[2:17]
	s_mov_b32 m0, s86
	s_waitcnt vmcnt(0) lgkmcnt(0)
	s_barrier
; DI void gemm_out(const Params& p, char* lds) {
;     ...
;         for (int kt = 0; kt < 16; ++kt) {
;             if (kt + 1 < 16) OSTAGE((kt + 1) & 1, kt + 1);
;             const char* sb = lds + (kt & 1) * 28672; const char* sa = sb + 16384;
; #pragma unroll
;             for (int ks = 0; ks < 2; ++ks) {
;                 bf16x8 fw[4], fx[3];
; #pragma unroll
;                 for (int ct = 0; ct < 4; ++ct) fw[ct] = *(const bf16x8*)(sb + swz(wn * 64 + ct * 16 + q, 4 * ks + g));
; #pragma unroll
;                 for (int tt = 0; tt < 3; ++tt) fx[tt] = *(const bf16x8*)(sa + swz(wm * 48 + tt * 16 + q, 4 * ks + g));
; #pragma unroll
;                 for (int ct = 0; ct < 4; ++ct)
; #pragma unroll
;                     for (int tt = 0; tt < 3; ++tt) acc[ct][tt] = __builtin_amdgcn_mfma_f32_16x16x32_bf16(fw[ct], fx[tt], acc[ct][tt], 0, 0, 0);
;             }
;             __syncthreads();
;         }
	ds_read_b128 v[102:105], v74 offset:16384
	ds_read_b128 v[106:109], v96
	ds_read_b128 v[110:113], v96 offset:4096
	ds_read_b128 v[114:117], v74 offset:20480
	v_mfma_f32_32x32x16_bf16 v[34:49], v[242:245], v[238:241], v[34:49]
	v_mfma_f32_32x32x16_bf16 v[18:33], v[246:249], v[238:241], v[18:33]
	v_lshl_add_u64 v[254:255], v[76:77], 0, s[24:25]
	global_load_lds_dwordx4 v[254:255], off
	v_lshl_add_u64 v[254:255], v[78:79], 0, s[24:25]
	s_mov_b32 m0, s87
	s_nop 0
	global_load_lds_dwordx4 v[254:255], off
	v_mfma_f32_32x32x16_bf16 v[50:65], v[242:245], v[250:253], v[50:65]
	v_lshl_add_u64 v[254:255], v[80:81], 0, s[24:25]
	s_mov_b32 m0, s88
	s_nop 0
	global_load_lds_dwordx4 v[254:255], off
	v_mfma_f32_32x32x16_bf16 v[2:17], v[246:249], v[250:253], v[2:17]
	s_waitcnt lgkmcnt(0)
	ds_read_b128 v[238:241], v95 offset:16384
	ds_read_b128 v[242:245], v97
	ds_read_b128 v[246:249], v97 offset:4096
	ds_read_b128 v[250:253], v95 offset:20480
	v_mfma_f32_32x32x16_bf16 v[34:49], v[106:109], v[102:105], v[34:49]
	v_lshl_add_u64 v[254:255], v[82:83], 0, s[24:25]
	s_mov_b32 m0, s89
	s_nop 0
	global_load_lds_dwordx4 v[254:255], off
	v_mfma_f32_32x32x16_bf16 v[18:33], v[110:113], v[102:105], v[18:33]
	v_lshl_add_u64 v[254:255], v[84:85], 0, s[24:25]
	s_mov_b32 m0, s91
	s_nop 0
	global_load_lds_dwordx4 v[254:255], off
	v_mfma_f32_32x32x16_bf16 v[50:65], v[106:109], v[114:117], v[50:65]
	v_mfma_f32_32x32x16_bf16 v[2:17], v[110:113], v[114:117], v[2:17]
	s_waitcnt lgkmcnt(0)
	ds_read_b128 v[102:105], v98 offset:16384
	ds_read_b128 v[106:109], v99
	ds_read_b128 v[110:113], v99 offset:4096
	ds_read_b128 v[114:117], v98 offset:20480
	v_mfma_f32_32x32x16_bf16 v[34:49], v[242:245], v[238:241], v[34:49]
	v_lshl_add_u64 v[254:255], v[86:87], 0, s[24:25]
	s_mov_b32 m0, s92
	s_nop 0
	global_load_lds_dwordx4 v[254:255], off
	v_mfma_f32_32x32x16_bf16 v[18:33], v[246:249], v[238:241], v[18:33]
	v_lshl_add_u64 v[254:255], v[88:89], 0, s[24:25]
	s_mov_b32 m0, s93
	s_nop 0
	global_load_lds_dwordx4 v[254:255], off
	v_mfma_f32_32x32x16_bf16 v[50:65], v[242:245], v[250:253], v[50:65]
	v_mfma_f32_32x32x16_bf16 v[2:17], v[246:249], v[250:253], v[2:17]
	s_waitcnt lgkmcnt(0)
	ds_read_b128 v[238:241], v100 offset:16384
	ds_read_b128 v[242:245], v101
	ds_read_b128 v[246:249], v101 offset:4096
	ds_read_b128 v[250:253], v100 offset:20480
	v_mfma_f32_32x32x16_bf16 v[34:49], v[106:109], v[102:105], v[34:49]
	v_lshl_add_u64 v[254:255], v[90:91], 0, s[24:25]
	s_mov_b32 m0, s94
	s_nop 0
	global_load_lds_dwordx4 v[254:255], off
	v_mfma_f32_32x32x16_bf16 v[18:33], v[110:113], v[102:105], v[18:33]
	v_mfma_f32_32x32x16_bf16 v[50:65], v[106:109], v[114:117], v[50:65]
	v_mfma_f32_32x32x16_bf16 v[2:17], v[110:113], v[114:117], v[2:17]
	s_mov_b32 m0, s1
	s_waitcnt vmcnt(0) lgkmcnt(0)
	s_barrier
	ds_read_b128 v[102:105], v74 offset:49152
	ds_read_b128 v[106:109], v96 offset:32768
	ds_read_b128 v[110:113], v96 offset:36864
	ds_read_b128 v[114:117], v74 offset:53248
	v_mfma_f32_32x32x16_bf16 v[34:49], v[242:245], v[238:241], v[34:49]
	v_mfma_f32_32x32x16_bf16 v[18:33], v[246:249], v[238:241], v[18:33]
	v_lshl_add_u64 v[254:255], v[76:77], 0, s[26:27]
	global_load_lds_dwordx4 v[254:255], off
	v_lshl_add_u64 v[254:255], v[78:79], 0, s[26:27]
	s_mov_b32 m0, s7
	s_nop 0
	global_load_lds_dwordx4 v[254:255], off
	v_mfma_f32_32x32x16_bf16 v[50:65], v[242:245], v[250:253], v[50:65]
	v_lshl_add_u64 v[254:255], v[80:81], 0, s[26:27]
	s_mov_b32 m0, s38
	s_nop 0
	global_load_lds_dwordx4 v[254:255], off
	v_mfma_f32_32x32x16_bf16 v[2:17], v[246:249], v[250:253], v[2:17]
	s_waitcnt lgkmcnt(0)
	ds_read_b128 v[238:241], v95 offset:49152
	ds_read_b128 v[242:245], v97 offset:32768
	ds_read_b128 v[246:249], v97 offset:36864
	ds_read_b128 v[250:253], v95 offset:53248
	v_mfma_f32_32x32x16_bf16 v[34:49], v[106:109], v[102:105], v[34:49]
	v_lshl_add_u64 v[254:255], v[82:83], 0, s[26:27]
	s_mov_b32 m0, s39
	s_nop 0
	global_load_lds_dwordx4 v[254:255], off
	v_mfma_f32_32x32x16_bf16 v[18:33], v[110:113], v[102:105], v[18:33]
	v_lshl_add_u64 v[254:255], v[84:85], 0, s[26:27]
	s_mov_b32 m0, s50
	s_nop 0
	global_load_lds_dwordx4 v[254:255], off
	v_mfma_f32_32x32x16_bf16 v[50:65], v[106:109], v[114:117], v[50:65]
	v_mfma_f32_32x32x16_bf16 v[2:17], v[110:113], v[114:117], v[2:17]
	s_waitcnt lgkmcnt(0)
	ds_read_b128 v[102:105], v98 offset:49152
	ds_read_b128 v[106:109], v99 offset:32768
	ds_read_b128 v[110:113], v99 offset:36864
	ds_read_b128 v[114:117], v98 offset:53248
	v_mfma_f32_32x32x16_bf16 v[34:49], v[242:245], v[238:241], v[34:49]
	v_lshl_add_u64 v[254:255], v[86:87], 0, s[26:27]
	s_mov_b32 m0, s51
	s_nop 0
	global_load_lds_dwordx4 v[254:255], off
	v_mfma_f32_32x32x16_bf16 v[18:33], v[246:249], v[238:241], v[18:33]
	v_lshl_add_u64 v[254:255], v[88:89], 0, s[26:27]
	s_mov_b32 m0, s83
	s_nop 0
	global_load_lds_dwordx4 v[254:255], off
	v_mfma_f32_32x32x16_bf16 v[50:65], v[242:245], v[250:253], v[50:65]
	v_mfma_f32_32x32x16_bf16 v[2:17], v[246:249], v[250:253], v[2:17]
	s_waitcnt lgkmcnt(0)
	ds_read_b128 v[238:241], v100 offset:49152
	ds_read_b128 v[242:245], v101 offset:32768
	ds_read_b128 v[246:249], v101 offset:36864
	ds_read_b128 v[250:253], v100 offset:53248
	v_mfma_f32_32x32x16_bf16 v[34:49], v[106:109], v[102:105], v[34:49]
	v_lshl_add_u64 v[254:255], v[90:91], 0, s[26:27]
	s_mov_b32 m0, s90
	s_nop 0
	global_load_lds_dwordx4 v[254:255], off
	v_mfma_f32_32x32x16_bf16 v[18:33], v[110:113], v[102:105], v[18:33]
	v_mfma_f32_32x32x16_bf16 v[50:65], v[106:109], v[114:117], v[50:65]
	v_mfma_f32_32x32x16_bf16 v[2:17], v[110:113], v[114:117], v[2:17]
	s_mov_b32 m0, s86
	s_waitcnt vmcnt(0) lgkmcnt(0)
	s_barrier
; DI void gemm_out(const Params& p, char* lds) {
;     ...
;         for (int kt = 0; kt < 16; ++kt) {
;             if (kt + 1 < 16) OSTAGE((kt + 1) & 1, kt + 1);
;             const char* sb = lds + (kt & 1) * 28672; const char* sa = sb + 16384;
; #pragma unroll
;             for (int ks = 0; ks < 2; ++ks) {
;                 bf16x8 fw[4], fx[3];
; #pragma unroll
;                 for (int ct = 0; ct < 4; ++ct) fw[ct] = *(const bf16x8*)(sb + swz(wn * 64 + ct * 16 + q, 4 * ks + g));
; #pragma unroll
;                 for (int tt = 0; tt < 3; ++tt) fx[tt] = *(const bf16x8*)(sa + swz(wm * 48 + tt * 16 + q, 4 * ks + g));
; #pragma unroll
;                 for (int ct = 0; ct < 4; ++ct)
; #pragma unroll
;                     for (int tt = 0; tt < 3; ++tt) acc[ct][tt] = __builtin_amdgcn_mfma_f32_16x16x32_bf16(fw[ct], fx[tt], acc[ct][tt], 0, 0, 0);
;             }
;             __syncthreads();
;         }
	ds_read_b128 v[102:105], v74 offset:16384
	ds_read_b128 v[106:109], v96
	ds_read_b128 v[110:113], v96 offset:4096
	ds_read_b128 v[114:117], v74 offset:20480
	v_mfma_f32_32x32x16_bf16 v[34:49], v[242:245], v[238:241], v[34:49]
	v_mfma_f32_32x32x16_bf16 v[18:33], v[246:249], v[238:241], v[18:33]
	v_lshl_add_u64 v[254:255], v[76:77], 0, s[28:29]
	global_load_lds_dwordx4 v[254:255], off
	v_lshl_add_u64 v[254:255], v[78:79], 0, s[28:29]
	s_mov_b32 m0, s87
	s_nop 0
	global_load_lds_dwordx4 v[254:255], off
	v_mfma_f32_32x32x16_bf16 v[50:65], v[242:245], v[250:253], v[50:65]
	v_lshl_add_u64 v[254:255], v[80:81], 0, s[28:29]
	s_mov_b32 m0, s88
	s_nop 0
	global_load_lds_dwordx4 v[254:255], off
	v_mfma_f32_32x32x16_bf16 v[2:17], v[246:249], v[250:253], v[2:17]
	s_waitcnt lgkmcnt(0)
	ds_read_b128 v[238:241], v95 offset:16384
	ds_read_b128 v[242:245], v97
	ds_read_b128 v[246:249], v97 offset:4096
	ds_read_b128 v[250:253], v95 offset:20480
	v_mfma_f32_32x32x16_bf16 v[34:49], v[106:109], v[102:105], v[34:49]
	v_lshl_add_u64 v[254:255], v[82:83], 0, s[28:29]
	s_mov_b32 m0, s89
	s_nop 0
	global_load_lds_dwordx4 v[254:255], off
	v_mfma_f32_32x32x16_bf16 v[18:33], v[110:113], v[102:105], v[18:33]
	v_lshl_add_u64 v[254:255], v[84:85], 0, s[28:29]
	s_mov_b32 m0, s91
	s_nop 0
	global_load_lds_dwordx4 v[254:255], off
	v_mfma_f32_32x32x16_bf16 v[50:65], v[106:109], v[114:117], v[50:65]
	v_mfma_f32_32x32x16_bf16 v[2:17], v[110:113], v[114:117], v[2:17]
	s_waitcnt lgkmcnt(0)
	ds_read_b128 v[102:105], v98 offset:16384
	ds_read_b128 v[106:109], v99
	ds_read_b128 v[110:113], v99 offset:4096
	ds_read_b128 v[114:117], v98 offset:20480
	v_mfma_f32_32x32x16_bf16 v[34:49], v[242:245], v[238:241], v[34:49]
	v_lshl_add_u64 v[254:255], v[86:87], 0, s[28:29]
	s_mov_b32 m0, s92
	s_nop 0
	global_load_lds_dwordx4 v[254:255], off
	v_mfma_f32_32x32x16_bf16 v[18:33], v[246:249], v[238:241], v[18:33]
	v_lshl_add_u64 v[254:255], v[88:89], 0, s[28:29]
	s_mov_b32 m0, s93
	s_nop 0
	global_load_lds_dwordx4 v[254:255], off
	v_mfma_f32_32x32x16_bf16 v[50:65], v[242:245], v[250:253], v[50:65]
	v_mfma_f32_32x32x16_bf16 v[2:17], v[246:249], v[250:253], v[2:17]
	s_waitcnt lgkmcnt(0)
	ds_read_b128 v[238:241], v100 offset:16384
	ds_read_b128 v[242:245], v101
	ds_read_b128 v[246:249], v101 offset:4096
	ds_read_b128 v[250:253], v100 offset:20480
	v_mfma_f32_32x32x16_bf16 v[34:49], v[106:109], v[102:105], v[34:49]
	v_lshl_add_u64 v[254:255], v[90:91], 0, s[28:29]
	s_mov_b32 m0, s94
	s_nop 0
	global_load_lds_dwordx4 v[254:255], off
	v_mfma_f32_32x32x16_bf16 v[18:33], v[110:113], v[102:105], v[18:33]
	v_mfma_f32_32x32x16_bf16 v[50:65], v[106:109], v[114:117], v[50:65]
	v_mfma_f32_32x32x16_bf16 v[2:17], v[110:113], v[114:117], v[2:17]
	s_mov_b32 m0, s1
	s_waitcnt vmcnt(0) lgkmcnt(0)
	s_barrier
	ds_read_b128 v[102:105], v74 offset:49152
	ds_read_b128 v[106:109], v96 offset:32768
	ds_read_b128 v[110:113], v96 offset:36864
	ds_read_b128 v[114:117], v74 offset:53248
	v_mfma_f32_32x32x16_bf16 v[34:49], v[242:245], v[238:241], v[34:49]
	v_mfma_f32_32x32x16_bf16 v[18:33], v[246:249], v[238:241], v[18:33]
	v_lshl_add_u64 v[254:255], v[76:77], 0, s[30:31]
	global_load_lds_dwordx4 v[254:255], off
	v_lshl_add_u64 v[254:255], v[78:79], 0, s[30:31]
	s_mov_b32 m0, s7
	s_nop 0
	global_load_lds_dwordx4 v[254:255], off
	v_mfma_f32_32x32x16_bf16 v[50:65], v[242:245], v[250:253], v[50:65]
	v_lshl_add_u64 v[254:255], v[80:81], 0, s[30:31]
	s_mov_b32 m0, s38
	s_nop 0
	global_load_lds_dwordx4 v[254:255], off
	v_mfma_f32_32x32x16_bf16 v[2:17], v[246:249], v[250:253], v[2:17]
	s_waitcnt lgkmcnt(0)
	ds_read_b128 v[238:241], v95 offset:49152
	ds_read_b128 v[242:245], v97 offset:32768
	ds_read_b128 v[246:249], v97 offset:36864
	ds_read_b128 v[250:253], v95 offset:53248
	v_mfma_f32_32x32x16_bf16 v[34:49], v[106:109], v[102:105], v[34:49]
	v_lshl_add_u64 v[254:255], v[82:83], 0, s[30:31]
	s_mov_b32 m0, s39
	s_nop 0
	global_load_lds_dwordx4 v[254:255], off
	v_mfma_f32_32x32x16_bf16 v[18:33], v[110:113], v[102:105], v[18:33]
	v_lshl_add_u64 v[254:255], v[84:85], 0, s[30:31]
	s_mov_b32 m0, s50
	s_nop 0
	global_load_lds_dwordx4 v[254:255], off
	v_mfma_f32_32x32x16_bf16 v[50:65], v[106:109], v[114:117], v[50:65]
	v_mfma_f32_32x32x16_bf16 v[2:17], v[110:113], v[114:117], v[2:17]
	s_waitcnt lgkmcnt(0)
	ds_read_b128 v[102:105], v98 offset:49152
	ds_read_b128 v[106:109], v99 offset:32768
	ds_read_b128 v[110:113], v99 offset:36864
	ds_read_b128 v[114:117], v98 offset:53248
	v_mfma_f32_32x32x16_bf16 v[34:49], v[242:245], v[238:241], v[34:49]
	v_lshl_add_u64 v[254:255], v[86:87], 0, s[30:31]
	s_mov_b32 m0, s51
	s_nop 0
	global_load_lds_dwordx4 v[254:255], off
	v_mfma_f32_32x32x16_bf16 v[18:33], v[246:249], v[238:241], v[18:33]
	v_lshl_add_u64 v[254:255], v[88:89], 0, s[30:31]
	s_mov_b32 m0, s83
	s_nop 0
	global_load_lds_dwordx4 v[254:255], off
	v_mfma_f32_32x32x16_bf16 v[50:65], v[242:245], v[250:253], v[50:65]
	v_mfma_f32_32x32x16_bf16 v[2:17], v[246:249], v[250:253], v[2:17]
	s_waitcnt lgkmcnt(0)
	ds_read_b128 v[238:241], v100 offset:49152
	ds_read_b128 v[242:245], v101 offset:32768
	ds_read_b128 v[246:249], v101 offset:36864
	ds_read_b128 v[250:253], v100 offset:53248
	v_mfma_f32_32x32x16_bf16 v[34:49], v[106:109], v[102:105], v[34:49]
	v_lshl_add_u64 v[254:255], v[90:91], 0, s[30:31]
	s_mov_b32 m0, s90
	s_nop 0
	global_load_lds_dwordx4 v[254:255], off
	v_mfma_f32_32x32x16_bf16 v[18:33], v[110:113], v[102:105], v[18:33]
	v_mfma_f32_32x32x16_bf16 v[50:65], v[106:109], v[114:117], v[50:65]
	v_mfma_f32_32x32x16_bf16 v[2:17], v[110:113], v[114:117], v[2:17]
	s_mov_b32 m0, s86
	s_waitcnt vmcnt(0) lgkmcnt(0)
	s_barrier
; DI void gemm_out(const Params& p, char* lds) {
;     ...
;         for (int kt = 0; kt < 16; ++kt) {
;             if (kt + 1 < 16) OSTAGE((kt + 1) & 1, kt + 1);
;             const char* sb = lds + (kt & 1) * 28672; const char* sa = sb + 16384;
; #pragma unroll
;             for (int ks = 0; ks < 2; ++ks) {
;                 bf16x8 fw[4], fx[3];
; #pragma unroll
;                 for (int ct = 0; ct < 4; ++ct) fw[ct] = *(const bf16x8*)(sb + swz(wn * 64 + ct * 16 + q, 4 * ks + g));
; #pragma unroll
;                 for (int tt = 0; tt < 3; ++tt) fx[tt] = *(const bf16x8*)(sa + swz(wm * 48 + tt * 16 + q, 4 * ks + g));
; #pragma unroll
;                 for (int ct = 0; ct < 4; ++ct)
; #pragma unroll
;                     for (int tt = 0; tt < 3; ++tt) acc[ct][tt] = __builtin_amdgcn_mfma_f32_16x16x32_bf16(fw[ct], fx[tt], acc[ct][tt], 0, 0, 0);
;             }
;             __syncthreads();
;         }
	ds_read_b128 v[102:105], v74 offset:16384
	ds_read_b128 v[106:109], v96
	ds_read_b128 v[110:113], v96 offset:4096
	ds_read_b128 v[114:117], v74 offset:20480
	v_mfma_f32_32x32x16_bf16 v[34:49], v[242:245], v[238:241], v[34:49]
	v_mfma_f32_32x32x16_bf16 v[18:33], v[246:249], v[238:241], v[18:33]
	v_lshl_add_u64 v[254:255], v[76:77], 0, s[36:37]
	global_load_lds_dwordx4 v[254:255], off
	v_lshl_add_u64 v[254:255], v[78:79], 0, s[36:37]
	s_mov_b32 m0, s87
	s_nop 0
	global_load_lds_dwordx4 v[254:255], off
	v_mfma_f32_32x32x16_bf16 v[50:65], v[242:245], v[250:253], v[50:65]
	v_lshl_add_u64 v[254:255], v[80:81], 0, s[36:37]
	s_mov_b32 m0, s88
	s_nop 0
	global_load_lds_dwordx4 v[254:255], off
	v_mfma_f32_32x32x16_bf16 v[2:17], v[246:249], v[250:253], v[2:17]
	s_waitcnt lgkmcnt(0)
	ds_read_b128 v[238:241], v95 offset:16384
	ds_read_b128 v[242:245], v97
	ds_read_b128 v[246:249], v97 offset:4096
	ds_read_b128 v[250:253], v95 offset:20480
	v_mfma_f32_32x32x16_bf16 v[34:49], v[106:109], v[102:105], v[34:49]
	v_lshl_add_u64 v[254:255], v[82:83], 0, s[36:37]
	s_mov_b32 m0, s89
	s_nop 0
	global_load_lds_dwordx4 v[254:255], off
	v_mfma_f32_32x32x16_bf16 v[18:33], v[110:113], v[102:105], v[18:33]
	v_lshl_add_u64 v[254:255], v[84:85], 0, s[36:37]
	s_mov_b32 m0, s91
	s_nop 0
	global_load_lds_dwordx4 v[254:255], off
	v_mfma_f32_32x32x16_bf16 v[50:65], v[106:109], v[114:117], v[50:65]
	v_mfma_f32_32x32x16_bf16 v[2:17], v[110:113], v[114:117], v[2:17]
	s_waitcnt lgkmcnt(0)
	ds_read_b128 v[102:105], v98 offset:16384
	ds_read_b128 v[106:109], v99
	ds_read_b128 v[110:113], v99 offset:4096
	ds_read_b128 v[114:117], v98 offset:20480
	v_mfma_f32_32x32x16_bf16 v[34:49], v[242:245], v[238:241], v[34:49]
	v_lshl_add_u64 v[254:255], v[86:87], 0, s[36:37]
	s_mov_b32 m0, s92
	s_nop 0
	global_load_lds_dwordx4 v[254:255], off
	v_mfma_f32_32x32x16_bf16 v[18:33], v[246:249], v[238:241], v[18:33]
	v_lshl_add_u64 v[254:255], v[88:89], 0, s[36:37]
	s_mov_b32 m0, s93
	s_nop 0
	global_load_lds_dwordx4 v[254:255], off
	v_mfma_f32_32x32x16_bf16 v[50:65], v[242:245], v[250:253], v[50:65]
	v_mfma_f32_32x32x16_bf16 v[2:17], v[246:249], v[250:253], v[2:17]
	s_waitcnt lgkmcnt(0)
	ds_read_b128 v[238:241], v100 offset:16384
	ds_read_b128 v[242:245], v101
	ds_read_b128 v[246:249], v101 offset:4096
	ds_read_b128 v[250:253], v100 offset:20480
	v_mfma_f32_32x32x16_bf16 v[34:49], v[106:109], v[102:105], v[34:49]
	v_lshl_add_u64 v[254:255], v[90:91], 0, s[36:37]
	s_mov_b32 m0, s94
	s_nop 0
	global_load_lds_dwordx4 v[254:255], off
	v_mfma_f32_32x32x16_bf16 v[18:33], v[110:113], v[102:105], v[18:33]
	v_mfma_f32_32x32x16_bf16 v[50:65], v[106:109], v[114:117], v[50:65]
	v_mfma_f32_32x32x16_bf16 v[2:17], v[110:113], v[114:117], v[2:17]
	s_mov_b32 m0, s1
	s_waitcnt vmcnt(0) lgkmcnt(0)
	s_barrier
	ds_read_b128 v[102:105], v74 offset:49152
	ds_read_b128 v[106:109], v96 offset:32768
	ds_read_b128 v[110:113], v96 offset:36864
	ds_read_b128 v[114:117], v74 offset:53248
	v_mfma_f32_32x32x16_bf16 v[34:49], v[242:245], v[238:241], v[34:49]
	v_mfma_f32_32x32x16_bf16 v[18:33], v[246:249], v[238:241], v[18:33]
	v_lshl_add_u64 v[254:255], v[76:77], 0, s[68:69]
	global_load_lds_dwordx4 v[254:255], off
	v_lshl_add_u64 v[254:255], v[78:79], 0, s[68:69]
	s_mov_b32 m0, s7
	v_lshl_add_u64 v[76:77], v[76:77], 0, s[70:71]
	global_load_lds_dwordx4 v[254:255], off
	v_mfma_f32_32x32x16_bf16 v[50:65], v[242:245], v[250:253], v[50:65]
	v_lshl_add_u64 v[254:255], v[80:81], 0, s[68:69]
	s_mov_b32 m0, s38
	s_nop 0
	global_load_lds_dwordx4 v[254:255], off
	v_mfma_f32_32x32x16_bf16 v[2:17], v[246:249], v[250:253], v[2:17]
	s_waitcnt lgkmcnt(0)
	ds_read_b128 v[238:241], v95 offset:49152
	ds_read_b128 v[242:245], v97 offset:32768
	ds_read_b128 v[246:249], v97 offset:36864
	ds_read_b128 v[250:253], v95 offset:53248
	v_mfma_f32_32x32x16_bf16 v[34:49], v[106:109], v[102:105], v[34:49]
	v_lshl_add_u64 v[254:255], v[82:83], 0, s[68:69]
	s_mov_b32 m0, s39
	s_nop 0
	global_load_lds_dwordx4 v[254:255], off
	v_mfma_f32_32x32x16_bf16 v[18:33], v[110:113], v[102:105], v[18:33]
	v_lshl_add_u64 v[254:255], v[84:85], 0, s[68:69]
	s_mov_b32 m0, s50
	s_nop 0
	global_load_lds_dwordx4 v[254:255], off
	v_mfma_f32_32x32x16_bf16 v[50:65], v[106:109], v[114:117], v[50:65]
	v_mfma_f32_32x32x16_bf16 v[2:17], v[110:113], v[114:117], v[2:17]
	s_waitcnt lgkmcnt(0)
	ds_read_b128 v[102:105], v98 offset:49152
	ds_read_b128 v[106:109], v99 offset:32768
	ds_read_b128 v[110:113], v99 offset:36864
	ds_read_b128 v[114:117], v98 offset:53248
	v_mfma_f32_32x32x16_bf16 v[34:49], v[242:245], v[238:241], v[34:49]
	v_lshl_add_u64 v[254:255], v[86:87], 0, s[68:69]
	s_mov_b32 m0, s51
	s_nop 0
	global_load_lds_dwordx4 v[254:255], off
	v_mfma_f32_32x32x16_bf16 v[18:33], v[246:249], v[238:241], v[18:33]
	v_lshl_add_u64 v[254:255], v[88:89], 0, s[68:69]
	s_mov_b32 m0, s83
	s_nop 0
	global_load_lds_dwordx4 v[254:255], off
	v_mfma_f32_32x32x16_bf16 v[50:65], v[242:245], v[250:253], v[50:65]
	v_mfma_f32_32x32x16_bf16 v[2:17], v[246:249], v[250:253], v[2:17]
	s_waitcnt lgkmcnt(0)
	ds_read_b128 v[238:241], v100 offset:49152
	ds_read_b128 v[242:245], v101 offset:32768
	ds_read_b128 v[246:249], v101 offset:36864
	ds_read_b128 v[250:253], v100 offset:53248
	v_mfma_f32_32x32x16_bf16 v[34:49], v[106:109], v[102:105], v[34:49]
	v_lshl_add_u64 v[254:255], v[90:91], 0, s[68:69]
	s_mov_b32 m0, s90
	s_nop 0
	global_load_lds_dwordx4 v[254:255], off
	v_mfma_f32_32x32x16_bf16 v[18:33], v[110:113], v[102:105], v[18:33]
	v_mfma_f32_32x32x16_bf16 v[50:65], v[106:109], v[114:117], v[50:65]
	v_mfma_f32_32x32x16_bf16 v[2:17], v[110:113], v[114:117], v[2:17]
	s_mov_b32 m0, s86
	s_mov_b32 s86, 0
	s_waitcnt vmcnt(0) lgkmcnt(0)
	s_barrier
; DI float4 ntld4(const float* p) { const f32x4 v = __builtin_nontemporal_load((const f32x4*)p); return (float4){v[0], v[1], v[2], v[3]}; }
; #define TILE_MN(t, M0, N0) do { int pan_ = (t) / (mtiles * 8); if (pan_ >= npan) pan_ = npan - 1; const int pw_ = (pan_ == npan - 1) ? ntiles - 8 * pan_ : 8; const int loc_ = (t) - pan_ * mtiles * 8; \
;         M0 = (loc_ / pw_) * 128; N0 = (8 * pan_ + loc_ % pw_) * 128; } while (0)
; template <class Epi>
; DI void gemm_phase(const u16* __restrict__ A, const u16* __restrict__ B, int mtiles, int ntiles, char* lds, const Epi& epi) {
;     ...
;         if (nxt < ntile) { TILE_MN(nxt, m1, n1); GSTAGE(0, 0, A + (size_t)m1 * 1024, B + (size_t)n1 * 1024); }
; DI void gemm_out(const Params& p, char* lds) {
;     ...
;         for (int tt = 0; tt < 3; ++tt) { const int row = m0 + wm * 48 + tt * 16 + q; const float* xr = row < NTP ? p.x_p + (size_t)row * DM : p.x_s + (size_t)(row - NTP) * DM;
; #pragma unroll
;             for (int ct = 0; ct < 4; ++ct) xres[tt][ct] = ntld4(xr + n0 + wn * 64 + ct * 16 + 4 * g); }
;         __syncthreads();
;         for (int kt = 0; kt < 16; ++kt) {
;             if (kt + 1 < 16) OSTAGE((kt + 1) & 1, kt + 1);
;             const char* sb = lds + (kt & 1) * 28672; const char* sa = sb + 16384;
; #pragma unroll
;             for (int ks = 0; ks < 2; ++ks) {
;                 bf16x8 fw[4], fx[3];
; #pragma unroll
;                 for (int ct = 0; ct < 4; ++ct) fw[ct] = *(const bf16x8*)(sb + swz(wn * 64 + ct * 16 + q, 4 * ks + g));
; #pragma unroll
;                 for (int tt = 0; tt < 3; ++tt) fx[tt] = *(const bf16x8*)(sa + swz(wm * 48 + tt * 16 + q, 4 * ks + g));
; #pragma unroll
;                 for (int ct = 0; ct < 4; ++ct)
; #pragma unroll
;                     for (int tt = 0; tt < 3; ++tt) acc[ct][tt] = __builtin_amdgcn_mfma_f32_16x16x32_bf16(fw[ct], fx[tt], acc[ct][tt], 0, 0, 0);
;             }
;             __syncthreads();
	global_load_lds_dwordx4 v[76:77], off
	v_lshl_add_u64 v[76:77], v[78:79], 0, s[70:71]
	s_mov_b32 m0, s87
	v_mfma_f32_32x32x16_bf16 v[34:49], v[242:245], v[238:241], v[34:49]
	global_load_lds_dwordx4 v[76:77], off
	v_lshl_add_u64 v[76:77], v[80:81], 0, s[70:71]
	s_mov_b32 m0, s88
	s_mov_b32 s88, 0
	global_load_lds_dwordx4 v[76:77], off
	v_lshl_add_u64 v[76:77], v[82:83], 0, s[70:71]
	s_mov_b32 m0, s89
	v_mfma_f32_32x32x16_bf16 v[18:33], v[246:249], v[238:241], v[18:33]
	global_load_lds_dwordx4 v[76:77], off
	v_lshl_add_u64 v[76:77], v[84:85], 0, s[70:71]
	s_mov_b32 m0, s91
	s_nop 0
	global_load_lds_dwordx4 v[76:77], off
	v_lshl_add_u64 v[76:77], v[86:87], 0, s[70:71]
	s_mov_b32 m0, s92
	v_mfma_f32_32x32x16_bf16 v[50:65], v[242:245], v[250:253], v[50:65]
	global_load_lds_dwordx4 v[76:77], off
	v_lshl_add_u64 v[76:77], v[88:89], 0, s[70:71]
	s_mov_b32 m0, s93
	s_nop 0
	global_load_lds_dwordx4 v[76:77], off
	v_lshl_add_u64 v[76:77], v[90:91], 0, s[70:71]
	s_mov_b32 m0, s94
	v_mfma_f32_32x32x16_bf16 v[2:17], v[246:249], v[250:253], v[2:17]
	global_load_lds_dwordx4 v[76:77], off
	ds_read_b128 v[76:79], v74 offset:16384
	ds_read_b128 v[80:83], v96
	ds_read_b128 v[84:87], v96 offset:4096
	ds_read_b128 v[88:91], v74 offset:20480
	s_waitcnt lgkmcnt(0)
	v_mfma_f32_32x32x16_bf16 v[34:49], v[80:83], v[76:79], v[34:49]
	v_mfma_f32_32x32x16_bf16 v[18:33], v[84:87], v[76:79], v[18:33]
	v_mfma_f32_32x32x16_bf16 v[50:65], v[80:83], v[88:91], v[50:65]
	v_mfma_f32_32x32x16_bf16 v[2:17], v[84:87], v[88:91], v[2:17]
	ds_read_b128 v[76:79], v95 offset:16384
	ds_read_b128 v[80:83], v97
	ds_read_b128 v[84:87], v97 offset:4096
	ds_read_b128 v[88:91], v95 offset:20480
	s_waitcnt lgkmcnt(0)
	v_mfma_f32_32x32x16_bf16 v[34:49], v[80:83], v[76:79], v[34:49]
	v_mfma_f32_32x32x16_bf16 v[18:33], v[84:87], v[76:79], v[18:33]
	v_mfma_f32_32x32x16_bf16 v[50:65], v[80:83], v[88:91], v[50:65]
	v_mfma_f32_32x32x16_bf16 v[2:17], v[84:87], v[88:91], v[2:17]
	ds_read_b128 v[76:79], v98 offset:16384
	ds_read_b128 v[80:83], v99
	ds_read_b128 v[84:87], v99 offset:4096
	ds_read_b128 v[88:91], v98 offset:20480
	s_waitcnt lgkmcnt(0)
	v_mfma_f32_32x32x16_bf16 v[34:49], v[80:83], v[76:79], v[34:49]
	v_mfma_f32_32x32x16_bf16 v[18:33], v[84:87], v[76:79], v[18:33]
	v_mfma_f32_32x32x16_bf16 v[50:65], v[80:83], v[88:91], v[50:65]
	v_mfma_f32_32x32x16_bf16 v[2:17], v[84:87], v[88:91], v[2:17]
	ds_read_b128 v[76:79], v100 offset:16384
	ds_read_b128 v[80:83], v101
	ds_read_b128 v[84:87], v101 offset:4096
	ds_read_b128 v[88:91], v100 offset:20480
	s_waitcnt vmcnt(0) lgkmcnt(0)
	s_barrier
	s_cbranch_scc1 .Lo_skipnext
	s_mov_b32 m0, s1
	s_lshr_b32 s86, s33, 3
	s_lshl_b32 s86, s86, 7
	s_and_b32 s88, s33, 7
	s_lshl_b32 s88, s88, 7
	s_ashr_i32 s87, s86, 31
	s_lshl_b64 s[92:93], s[86:87], 11
	s_add_u32 s92, s54, s92
	s_addc_u32 s93, s55, s93
	s_ashr_i32 s89, s88, 31
	s_lshl_b64 s[94:95], s[88:89], 11
	v_readlane_b32 s1, v236, 9
	s_add_u32 s94, s1, s94
	v_readlane_b32 s1, v236, 11
	s_addc_u32 s95, s1, s95
	v_lshl_add_u64 v[118:119], s[92:93], 0, v[66:67]
	global_load_lds_dwordx4 v[118:119], off
	v_lshl_add_u64 v[66:67], s[94:95], 0, v[66:67]
	s_mov_b32 m0, s7
	s_nop 0
	global_load_lds_dwordx4 v[66:67], off
	v_lshl_add_u64 v[66:67], s[92:93], 0, v[68:69]
	s_mov_b32 m0, s38
	s_nop 0
	global_load_lds_dwordx4 v[66:67], off
	v_lshl_add_u64 v[66:67], s[94:95], 0, v[68:69]
	s_mov_b32 m0, s39
	s_nop 0
	global_load_lds_dwordx4 v[66:67], off
	v_lshl_add_u64 v[66:67], s[92:93], 0, v[70:71]
	s_mov_b32 m0, s50
	s_nop 0
	global_load_lds_dwordx4 v[66:67], off
	v_lshl_add_u64 v[66:67], s[94:95], 0, v[70:71]
	s_mov_b32 m0, s51
	s_nop 0
	global_load_lds_dwordx4 v[66:67], off
	v_lshl_add_u64 v[66:67], s[92:93], 0, v[72:73]
	s_mov_b32 m0, s83
	s_nop 0
	global_load_lds_dwordx4 v[66:67], off
	v_lshl_add_u64 v[66:67], s[94:95], 0, v[72:73]
	s_mov_b32 m0, s90
	s_nop 0
	global_load_lds_dwordx4 v[66:67], off
.Lo_skipnext:
	v_readfirstlane_b32 s96, v0
	s_lshr_b32 s96, s96, 6
	s_lshr_b32 s98, s96, 1
	s_and_b32 s96, s96, 1
	s_lshl_b32 s97, s96, 6
	s_add_i32 s97, s97, s82
	s_cmp_lt_u32 s82, 0x4000
	s_cselect_b32 s2, s56, s58
	s_cselect_b32 s3, s57, s59
	s_cselect_b32 s99, 0, 0x4000
	s_sub_i32 s99, s97, s99
	s_lshl_b32 s98, s98, 6
	s_add_i32 s98, s98, s0
	v_and_b32_e32 v184, 31, v0
	v_bfe_u32 v185, v0, 5, 1
	v_lshlrev_b32_e32 v185, 14, v185
	v_add_u32_e32 v186, s98, v184
	v_lshl_add_u32 v186, v186, 2, v185
	s_lshl_b32 s97, s97, 12
	s_lshl_b32 s99, s99, 12
	v_add_u32_e32 v188, s97, v186
	v_add_u32_e32 v187, s99, v186
	v_mfma_f32_32x32x16_bf16 v[34:49], v[80:83], v[76:79], v[34:49]
	global_load_dword v120, v187, s[2:3] nt
	global_load_dword v121, v187, s[2:3] offset:128 nt
	v_add_u32_e32 v187, 0x1000, v187
	global_load_dword v122, v187, s[2:3] nt
	global_load_dword v123, v187, s[2:3] offset:128 nt
	v_add_u32_e32 v187, 0x1000, v187
	v_mfma_f32_32x32x16_bf16 v[18:33], v[84:87], v[76:79], v[18:33]
	global_load_dword v124, v187, s[2:3] nt
	global_load_dword v125, v187, s[2:3] offset:128 nt
	v_add_u32_e32 v187, 0x1000, v187
	global_load_dword v126, v187, s[2:3] nt
	global_load_dword v127, v187, s[2:3] offset:128 nt
	v_add_u32_e32 v187, 0x5000, v187
	v_mfma_f32_32x32x16_bf16 v[50:65], v[80:83], v[88:91], v[50:65]
	global_load_dword v128, v187, s[2:3] nt
	global_load_dword v129, v187, s[2:3] offset:128 nt
	v_add_u32_e32 v187, 0x1000, v187
	global_load_dword v130, v187, s[2:3] nt
	global_load_dword v131, v187, s[2:3] offset:128 nt
	v_add_u32_e32 v187, 0x1000, v187
	v_mfma_f32_32x32x16_bf16 v[2:17], v[84:87], v[88:91], v[2:17]
	global_load_dword v132, v187, s[2:3] nt
	global_load_dword v133, v187, s[2:3] offset:128 nt
	v_add_u32_e32 v187, 0x1000, v187
	global_load_dword v134, v187, s[2:3] nt
	global_load_dword v135, v187, s[2:3] offset:128 nt
	v_add_u32_e32 v187, 0x5000, v187
	ds_read_b128 v[76:79], v96 offset:32768
	ds_read_b128 v[80:83], v96 offset:36864
	ds_read_b128 v[84:87], v74 offset:49152
	ds_read_b128 v[88:91], v74 offset:53248
	s_waitcnt lgkmcnt(1)
; DI float4 ntld4(const float* p) { const f32x4 v = __builtin_nontemporal_load((const f32x4*)p); return (float4){v[0], v[1], v[2], v[3]}; }
; DI void gemm_out(const Params& p, char* lds) {
;     ...
;         for (int tt = 0; tt < 3; ++tt) { const int row = m0 + wm * 48 + tt * 16 + q; const float* xr = row < NTP ? p.x_p + (size_t)row * DM : p.x_s + (size_t)(row - NTP) * DM;
; #pragma unroll
;             for (int ct = 0; ct < 4; ++ct) xres[tt][ct] = ntld4(xr + n0 + wn * 64 + ct * 16 + 4 * g); }
;         __syncthreads();
;         for (int kt = 0; kt < 16; ++kt) {
;             if (kt + 1 < 16) OSTAGE((kt + 1) & 1, kt + 1);
;             const char* sb = lds + (kt & 1) * 28672; const char* sa = sb + 16384;
; #pragma unroll
;             for (int ks = 0; ks < 2; ++ks) {
;                 bf16x8 fw[4], fx[3];
; #pragma unroll
;                 for (int ct = 0; ct < 4; ++ct) fw[ct] = *(const bf16x8*)(sb + swz(wn * 64 + ct * 16 + q, 4 * ks + g));
; #pragma unroll
;                 for (int tt = 0; tt < 3; ++tt) fx[tt] = *(const bf16x8*)(sa + swz(wm * 48 + tt * 16 + q, 4 * ks + g));
; #pragma unroll
;                 for (int ct = 0; ct < 4; ++ct)
; #pragma unroll
;                     for (int tt = 0; tt < 3; ++tt) acc[ct][tt] = __builtin_amdgcn_mfma_f32_16x16x32_bf16(fw[ct], fx[tt], acc[ct][tt], 0, 0, 0);
;             }
	v_mfma_f32_32x32x16_bf16 v[34:49], v[76:79], v[84:87], v[34:49]
	global_load_dword v136, v187, s[2:3] nt
	global_load_dword v137, v187, s[2:3] offset:128 nt
	v_add_u32_e32 v187, 0x1000, v187
	global_load_dword v138, v187, s[2:3] nt
	global_load_dword v139, v187, s[2:3] offset:128 nt
	v_add_u32_e32 v187, 0x1000, v187
	v_mfma_f32_32x32x16_bf16 v[18:33], v[80:83], v[84:87], v[18:33]
	global_load_dword v140, v187, s[2:3] nt
	global_load_dword v141, v187, s[2:3] offset:128 nt
	v_add_u32_e32 v187, 0x1000, v187
	global_load_dword v142, v187, s[2:3] nt
	global_load_dword v143, v187, s[2:3] offset:128 nt
	v_add_u32_e32 v187, 0x5000, v187
	s_waitcnt lgkmcnt(0)
	v_mfma_f32_32x32x16_bf16 v[50:65], v[76:79], v[88:91], v[50:65]
	global_load_dword v144, v187, s[2:3] nt
	global_load_dword v145, v187, s[2:3] offset:128 nt
	v_add_u32_e32 v187, 0x1000, v187
	global_load_dword v146, v187, s[2:3] nt
	global_load_dword v147, v187, s[2:3] offset:128 nt
	v_add_u32_e32 v187, 0x1000, v187
	v_mfma_f32_32x32x16_bf16 v[2:17], v[80:83], v[88:91], v[2:17]
	global_load_dword v148, v187, s[2:3] nt
	global_load_dword v149, v187, s[2:3] offset:128 nt
	v_add_u32_e32 v187, 0x1000, v187
	global_load_dword v150, v187, s[2:3] nt
	global_load_dword v151, v187, s[2:3] offset:128 nt
	v_add_u32_e32 v187, 0x5000, v187
	ds_read_b128 v[76:79], v95 offset:49152
	ds_read_b128 v[80:83], v97 offset:32768
	ds_read_b128 v[84:87], v97 offset:36864
	ds_read_b128 v[88:91], v95 offset:53248
	s_waitcnt lgkmcnt(2)
	v_mfma_f32_32x32x16_bf16 v[34:49], v[80:83], v[76:79], v[34:49]
	global_load_dword v152, v187, s[2:3] nt
	global_load_dword v153, v187, s[2:3] offset:128 nt
	v_add_u32_e32 v187, 0x1000, v187
	global_load_dword v154, v187, s[2:3] nt
	global_load_dword v155, v187, s[2:3] offset:128 nt
	v_add_u32_e32 v187, 0x1000, v187
	s_waitcnt lgkmcnt(1)
	v_mfma_f32_32x32x16_bf16 v[18:33], v[84:87], v[76:79], v[18:33]
	global_load_dword v156, v187, s[2:3] nt
	global_load_dword v157, v187, s[2:3] offset:128 nt
	v_add_u32_e32 v187, 0x1000, v187
	global_load_dword v158, v187, s[2:3] nt
	global_load_dword v159, v187, s[2:3] offset:128 nt
	v_add_u32_e32 v187, 0x5000, v187
	s_waitcnt lgkmcnt(0)
	v_mfma_f32_32x32x16_bf16 v[50:65], v[80:83], v[88:91], v[50:65]
	global_load_dword v160, v187, s[2:3] nt
	global_load_dword v161, v187, s[2:3] offset:128 nt
	v_add_u32_e32 v187, 0x1000, v187
	global_load_dword v162, v187, s[2:3] nt
	global_load_dword v163, v187, s[2:3] offset:128 nt
	v_add_u32_e32 v187, 0x1000, v187
	v_mfma_f32_32x32x16_bf16 v[2:17], v[84:87], v[88:91], v[2:17]
	global_load_dword v164, v187, s[2:3] nt
	global_load_dword v165, v187, s[2:3] offset:128 nt
	v_add_u32_e32 v187, 0x1000, v187
	global_load_dword v166, v187, s[2:3] nt
	global_load_dword v167, v187, s[2:3] offset:128 nt
	v_add_u32_e32 v187, 0x5000, v187
	ds_read_b128 v[76:79], v98 offset:49152
	ds_read_b128 v[80:83], v99 offset:32768
	ds_read_b128 v[84:87], v99 offset:36864
	ds_read_b128 v[88:91], v98 offset:53248
	s_waitcnt lgkmcnt(2)
	v_mfma_f32_32x32x16_bf16 v[34:49], v[80:83], v[76:79], v[34:49]
	global_load_dword v168, v187, s[2:3] nt
	global_load_dword v169, v187, s[2:3] offset:128 nt
	v_add_u32_e32 v187, 0x1000, v187
	global_load_dword v170, v187, s[2:3] nt
	global_load_dword v171, v187, s[2:3] offset:128 nt
	v_add_u32_e32 v187, 0x1000, v187
	s_waitcnt lgkmcnt(1)
	v_mfma_f32_32x32x16_bf16 v[18:33], v[84:87], v[76:79], v[18:33]
	global_load_dword v172, v187, s[2:3] nt
	global_load_dword v173, v187, s[2:3] offset:128 nt
	v_add_u32_e32 v187, 0x1000, v187
	global_load_dword v174, v187, s[2:3] nt
	global_load_dword v175, v187, s[2:3] offset:128 nt
	v_add_u32_e32 v187, 0x5000, v187
	s_waitcnt lgkmcnt(0)
	v_mfma_f32_32x32x16_bf16 v[50:65], v[80:83], v[88:91], v[50:65]
	global_load_dword v176, v187, s[2:3] nt
	global_load_dword v177, v187, s[2:3] offset:128 nt
	v_add_u32_e32 v187, 0x1000, v187
	global_load_dword v178, v187, s[2:3] nt
	global_load_dword v179, v187, s[2:3] offset:128 nt
	v_add_u32_e32 v187, 0x1000, v187
	v_mfma_f32_32x32x16_bf16 v[2:17], v[84:87], v[88:91], v[2:17]
	global_load_dword v180, v187, s[2:3] nt
	global_load_dword v181, v187, s[2:3] offset:128 nt
	v_add_u32_e32 v187, 0x1000, v187
	global_load_dword v182, v187, s[2:3] nt
	global_load_dword v183, v187, s[2:3] offset:128 nt
	ds_read_b128 v[76:79], v100 offset:49152
	ds_read_b128 v[80:83], v101 offset:32768
	ds_read_b128 v[84:87], v101 offset:36864
	ds_read_b128 v[88:91], v100 offset:53248
	s_waitcnt lgkmcnt(0)
	s_barrier
; DI void gemm_out(const Params& p, char* lds) {
;     ...
; #pragma unroll
;         for (int tt = 0; tt < 3; ++tt) {
;             const int row = m0 + wm * 48 + tt * 16 + q;
;             const float* xr = row < NTP ? p.x_p + (size_t)row * DM : p.x_s + (size_t)(row - NTP) * DM;
;             float* o = p.out + (size_t)row * DM;
; #pragma unroll
;             for (int ct = 0; ct < 4; ++ct) { const int col = n0 + wn * 64 + ct * 16 + 4 * g; const float4 xv = xres[tt][ct];
;                 const f32x4 w = {xv.x + acc[ct][tt][0], xv.y + acc[ct][tt][1], xv.z + acc[ct][tt][2], xv.w + acc[ct][tt][3]}; __builtin_nontemporal_store(w, (f32x4*)(o + col)); }
	v_mfma_f32_32x32x16_bf16 v[34:49], v[80:83], v[76:79], v[34:49]
	v_mfma_f32_32x32x16_bf16 v[18:33], v[84:87], v[76:79], v[18:33]
	v_mfma_f32_32x32x16_bf16 v[50:65], v[80:83], v[88:91], v[50:65]
	v_mfma_f32_32x32x16_bf16 v[2:17], v[84:87], v[88:91], v[2:17]
	s_nop 11
	s_waitcnt vmcnt(63)
	v_add_f32_e32 v34, v34, v120
	global_store_dword v188, v34, s[52:53] nt
	s_waitcnt vmcnt(63)
	v_add_f32_e32 v50, v50, v121
	global_store_dword v188, v50, s[52:53] offset:128 nt
	v_add_u32_e32 v188, 0x1000, v188
	s_waitcnt vmcnt(63)
	v_add_f32_e32 v35, v35, v122
	global_store_dword v188, v35, s[52:53] nt
	s_waitcnt vmcnt(63)
	v_add_f32_e32 v51, v51, v123
	global_store_dword v188, v51, s[52:53] offset:128 nt
	v_add_u32_e32 v188, 0x1000, v188
	s_waitcnt vmcnt(63)
	v_add_f32_e32 v36, v36, v124
	global_store_dword v188, v36, s[52:53] nt
	s_waitcnt vmcnt(63)
	v_add_f32_e32 v52, v52, v125
	global_store_dword v188, v52, s[52:53] offset:128 nt
	v_add_u32_e32 v188, 0x1000, v188
	s_waitcnt vmcnt(63)
	v_add_f32_e32 v37, v37, v126
	global_store_dword v188, v37, s[52:53] nt
	s_waitcnt vmcnt(63)
	v_add_f32_e32 v53, v53, v127
	global_store_dword v188, v53, s[52:53] offset:128 nt
	v_add_u32_e32 v188, 0x5000, v188
	s_waitcnt vmcnt(63)
	v_add_f32_e32 v38, v38, v128
	global_store_dword v188, v38, s[52:53] nt
	s_waitcnt vmcnt(63)
	v_add_f32_e32 v54, v54, v129
	global_store_dword v188, v54, s[52:53] offset:128 nt
	v_add_u32_e32 v188, 0x1000, v188
	s_waitcnt vmcnt(63)
	v_add_f32_e32 v39, v39, v130
	global_store_dword v188, v39, s[52:53] nt
	s_waitcnt vmcnt(63)
	v_add_f32_e32 v55, v55, v131
	global_store_dword v188, v55, s[52:53] offset:128 nt
	v_add_u32_e32 v188, 0x1000, v188
	s_waitcnt vmcnt(63)
	v_add_f32_e32 v40, v40, v132
	global_store_dword v188, v40, s[52:53] nt
	s_waitcnt vmcnt(63)
	v_add_f32_e32 v56, v56, v133
	global_store_dword v188, v56, s[52:53] offset:128 nt
	v_add_u32_e32 v188, 0x1000, v188
	s_waitcnt vmcnt(63)
	v_add_f32_e32 v41, v41, v134
	global_store_dword v188, v41, s[52:53] nt
	s_waitcnt vmcnt(63)
	v_add_f32_e32 v57, v57, v135
	global_store_dword v188, v57, s[52:53] offset:128 nt
	v_add_u32_e32 v188, 0x5000, v188
	s_waitcnt vmcnt(63)
	v_add_f32_e32 v42, v42, v136
	global_store_dword v188, v42, s[52:53] nt
	s_waitcnt vmcnt(63)
	v_add_f32_e32 v58, v58, v137
	global_store_dword v188, v58, s[52:53] offset:128 nt
	v_add_u32_e32 v188, 0x1000, v188
	s_waitcnt vmcnt(63)
	v_add_f32_e32 v43, v43, v138
	global_store_dword v188, v43, s[52:53] nt
	s_waitcnt vmcnt(63)
	v_add_f32_e32 v59, v59, v139
	global_store_dword v188, v59, s[52:53] offset:128 nt
	v_add_u32_e32 v188, 0x1000, v188
	s_waitcnt vmcnt(63)
	v_add_f32_e32 v44, v44, v140
	global_store_dword v188, v44, s[52:53] nt
	s_waitcnt vmcnt(63)
	v_add_f32_e32 v60, v60, v141
	global_store_dword v188, v60, s[52:53] offset:128 nt
	v_add_u32_e32 v188, 0x1000, v188
	s_waitcnt vmcnt(63)
	v_add_f32_e32 v45, v45, v142
	global_store_dword v188, v45, s[52:53] nt
	s_waitcnt vmcnt(63)
	v_add_f32_e32 v61, v61, v143
	global_store_dword v188, v61, s[52:53] offset:128 nt
	v_add_u32_e32 v188, 0x5000, v188
	s_waitcnt vmcnt(63)
	v_add_f32_e32 v46, v46, v144
	global_store_dword v188, v46, s[52:53] nt
	s_waitcnt vmcnt(63)
	v_add_f32_e32 v62, v62, v145
	global_store_dword v188, v62, s[52:53] offset:128 nt
	v_add_u32_e32 v188, 0x1000, v188
	s_waitcnt vmcnt(63)
	v_add_f32_e32 v47, v47, v146
	global_store_dword v188, v47, s[52:53] nt
	s_waitcnt vmcnt(63)
	v_add_f32_e32 v63, v63, v147
	global_store_dword v188, v63, s[52:53] offset:128 nt
	v_add_u32_e32 v188, 0x1000, v188
	s_waitcnt vmcnt(63)
	v_add_f32_e32 v48, v48, v148
	global_store_dword v188, v48, s[52:53] nt
	s_waitcnt vmcnt(63)
	v_add_f32_e32 v64, v64, v149
	global_store_dword v188, v64, s[52:53] offset:128 nt
	v_add_u32_e32 v188, 0x1000, v188
	s_waitcnt vmcnt(63)
	v_add_f32_e32 v49, v49, v150
	global_store_dword v188, v49, s[52:53] nt
	s_waitcnt vmcnt(63)
	v_add_f32_e32 v65, v65, v151
	global_store_dword v188, v65, s[52:53] offset:128 nt
	v_add_u32_e32 v188, 0x5000, v188
	s_waitcnt vmcnt(63)
	v_add_f32_e32 v18, v18, v152
	global_store_dword v188, v18, s[52:53] nt
	s_waitcnt vmcnt(63)
	v_add_f32_e32 v2, v2, v153
	global_store_dword v188, v2, s[52:53] offset:128 nt
	v_add_u32_e32 v188, 0x1000, v188
	s_waitcnt vmcnt(63)
	v_add_f32_e32 v19, v19, v154
	global_store_dword v188, v19, s[52:53] nt
	s_waitcnt vmcnt(63)
	v_add_f32_e32 v3, v3, v155
	global_store_dword v188, v3, s[52:53] offset:128 nt
	v_add_u32_e32 v188, 0x1000, v188
	s_waitcnt vmcnt(63)
	v_add_f32_e32 v20, v20, v156
	global_store_dword v188, v20, s[52:53] nt
	s_waitcnt vmcnt(63)
	v_add_f32_e32 v4, v4, v157
	global_store_dword v188, v4, s[52:53] offset:128 nt
	v_add_u32_e32 v188, 0x1000, v188
	s_waitcnt vmcnt(63)
	v_add_f32_e32 v21, v21, v158
	global_store_dword v188, v21, s[52:53] nt
	s_waitcnt vmcnt(63)
	v_add_f32_e32 v5, v5, v159
	global_store_dword v188, v5, s[52:53] offset:128 nt
	v_add_u32_e32 v188, 0x5000, v188
	s_waitcnt vmcnt(63)
	v_add_f32_e32 v22, v22, v160
	global_store_dword v188, v22, s[52:53] nt
	s_waitcnt vmcnt(63)
	v_add_f32_e32 v6, v6, v161
	global_store_dword v188, v6, s[52:53] offset:128 nt
	v_add_u32_e32 v188, 0x1000, v188
	s_waitcnt vmcnt(63)
	v_add_f32_e32 v23, v23, v162
	global_store_dword v188, v23, s[52:53] nt
	s_waitcnt vmcnt(63)
	v_add_f32_e32 v7, v7, v163
	global_store_dword v188, v7, s[52:53] offset:128 nt
	v_add_u32_e32 v188, 0x1000, v188
	s_waitcnt vmcnt(63)
	v_add_f32_e32 v24, v24, v164
	global_store_dword v188, v24, s[52:53] nt
	s_waitcnt vmcnt(63)
	v_add_f32_e32 v8, v8, v165
	global_store_dword v188, v8, s[52:53] offset:128 nt
	v_add_u32_e32 v188, 0x1000, v188
	s_waitcnt vmcnt(63)
; DI void gemm_out(const Params& p, char* lds) {
;     ...
;     for (int tile = vb; tile < ntile; tile += gridDim.x) {
;         int tid = threadIdx.x; asm volatile("" : "+v"(tid));
;         const int lane = tid & 63, wave = __builtin_amdgcn_readfirstlane(tid >> 6); const int wn = wave >> 1, wm = wave & 1; const int q = lane & 15, g = lane >> 4;
;         const int mt = tile >> 3, nt = tile & 7; const int m0 = mt * 96, n0 = nt * 128;
;         f32x4 acc[4][3];
; #pragma unroll
;         for (int a = 0; a < 4; ++a)
; #pragma unroll
;             for (int b = 0; b < 3; ++b) acc[a][b] = (f32x4){0.f, 0.f, 0.f, 0.f};
;         unsigned soffb[4], soffa[3];
; #pragma unroll
;         for (int i = 0; i < 4; ++i) { const int row = 8 * (i * 4 + wave) + (lane >> 3); const int ch = (lane & 7) ^ ((row >> 1) & 7); soffb[i] = (unsigned)(row * 1024 + ch * 8); }
; #pragma unroll
;         for (int i = 0; i < 3; ++i) { const int row = 8 * (i * 4 + wave) + (lane >> 3); const int ch = (lane & 7) ^ ((row >> 1) & 7); soffa[i] = (unsigned)(row * 1024 + ch * 8); }
;         const u16* ga = A + (size_t)m0 * 1024; const u16* gb = B + (size_t)n0 * 1024;
;     ...
;         OSTAGE(0, 0);
;     ...
; #pragma unroll
;         for (int tt = 0; tt < 3; ++tt) {
;             const int row = m0 + wm * 48 + tt * 16 + q;
;             const float* xr = row < NTP ? p.x_p + (size_t)row * DM : p.x_s + (size_t)(row - NTP) * DM;
;             float* o = p.out + (size_t)row * DM;
; #pragma unroll
;             for (int ct = 0; ct < 4; ++ct) { const int col = n0 + wn * 64 + ct * 16 + 4 * g; const float4 xv = xres[tt][ct];
;                 const f32x4 w = {xv.x + acc[ct][tt][0], xv.y + acc[ct][tt][1], xv.z + acc[ct][tt][2], xv.w + acc[ct][tt][3]}; __builtin_nontemporal_store(w, (f32x4*)(o + col)); }
	v_add_f32_e32 v25, v25, v166
	global_store_dword v188, v25, s[52:53] nt
	s_waitcnt vmcnt(63)
	v_add_f32_e32 v9, v9, v167
	global_store_dword v188, v9, s[52:53] offset:128 nt
	v_add_u32_e32 v188, 0x5000, v188
	s_waitcnt vmcnt(63)
	v_add_f32_e32 v26, v26, v168
	global_store_dword v188, v26, s[52:53] nt
	s_waitcnt vmcnt(63)
	v_add_f32_e32 v10, v10, v169
	global_store_dword v188, v10, s[52:53] offset:128 nt
	v_add_u32_e32 v188, 0x1000, v188
	s_waitcnt vmcnt(63)
	v_add_f32_e32 v27, v27, v170
	global_store_dword v188, v27, s[52:53] nt
	s_waitcnt vmcnt(63)
	v_add_f32_e32 v11, v11, v171
	global_store_dword v188, v11, s[52:53] offset:128 nt
	v_add_u32_e32 v188, 0x1000, v188
	s_waitcnt vmcnt(63)
	v_add_f32_e32 v28, v28, v172
	global_store_dword v188, v28, s[52:53] nt
	s_waitcnt vmcnt(63)
	v_add_f32_e32 v12, v12, v173
	global_store_dword v188, v12, s[52:53] offset:128 nt
	v_add_u32_e32 v188, 0x1000, v188
	s_waitcnt vmcnt(63)
	v_add_f32_e32 v29, v29, v174
	global_store_dword v188, v29, s[52:53] nt
	s_waitcnt vmcnt(63)
	v_add_f32_e32 v13, v13, v175
	global_store_dword v188, v13, s[52:53] offset:128 nt
	v_add_u32_e32 v188, 0x5000, v188
	s_waitcnt vmcnt(63)
	v_add_f32_e32 v30, v30, v176
	global_store_dword v188, v30, s[52:53] nt
	s_waitcnt vmcnt(63)
	v_add_f32_e32 v14, v14, v177
	global_store_dword v188, v14, s[52:53] offset:128 nt
	v_add_u32_e32 v188, 0x1000, v188
	s_waitcnt vmcnt(63)
	v_add_f32_e32 v31, v31, v178
	global_store_dword v188, v31, s[52:53] nt
	s_waitcnt vmcnt(63)
	v_add_f32_e32 v15, v15, v179
	global_store_dword v188, v15, s[52:53] offset:128 nt
	v_add_u32_e32 v188, 0x1000, v188
	s_waitcnt vmcnt(63)
	v_add_f32_e32 v32, v32, v180
	global_store_dword v188, v32, s[52:53] nt
	s_waitcnt vmcnt(63)
	v_add_f32_e32 v16, v16, v181
	global_store_dword v188, v16, s[52:53] offset:128 nt
	v_add_u32_e32 v188, 0x1000, v188
	s_waitcnt vmcnt(63)
	v_add_f32_e32 v33, v33, v182
	global_store_dword v188, v33, s[52:53] nt
	s_waitcnt vmcnt(63)
	v_add_f32_e32 v17, v17, v183
	global_store_dword v188, v17, s[52:53] offset:128 nt
	v_readlane_b32 s95, v236, 8
	s_cmpk_lt_i32 s33, 0x400
	s_mov_b32 s0, s88
	s_mov_b32 s82, s86
	s_cbranch_scc1 .Lo_tile
	s_cmp_gt_u32 s64, 0x7f
	s_cbranch_scc1 .LBB0_578
	s_lshr_b32 s4, s64, 4
	s_lshl_b32 s4, s4, 6
	s_add_i32 s4, s4, 0x4000
	s_and_b32 s5, s64, 15
	s_lshl_b32 s5, s5, 6
	v_readfirstlane_b32 s6, v0
	s_lshr_b32 s6, s6, 6
	s_and_b32 s7, s6, 1
	s_lshr_b32 s8, s6, 1
	s_lshl_b32 s1, s6, 10
	s_lshl_b32 s9, s7, 5
	s_add_i32 s9, s9, s4
	s_lshl_b32 s20, s8, 5
	s_add_i32 s20, s20, s5
	v_and_b32_e32 v24, 31, v0
	v_bfe_u32 v21, v0, 5, 1
	v_add_u32_e32 v23, s20, v24
	v_lshlrev_b32_e32 v34, 14, v21
	v_lshl_add_u32 v34, v23, 2, v34
	s_lshl_b32 s21, s9, 12
	s_sub_i32 s22, s9, 0x4000
	s_lshl_b32 s22, s22, 12
	v_add_u32_e32 v35, s21, v34
	v_add_u32_e32 v34, s22, v34
	global_load_dword v40, v34, s[58:59] nt
	v_add_u32_e32 v34, 0x1000, v34
	global_load_dword v41, v34, s[58:59] nt
	v_add_u32_e32 v34, 0x1000, v34
	global_load_dword v42, v34, s[58:59] nt
	v_add_u32_e32 v34, 0x1000, v34
	global_load_dword v43, v34, s[58:59] nt
	v_add_u32_e32 v34, 0x5000, v34
	global_load_dword v44, v34, s[58:59] nt
	v_add_u32_e32 v34, 0x1000, v34
	global_load_dword v45, v34, s[58:59] nt
	v_add_u32_e32 v34, 0x1000, v34
	global_load_dword v46, v34, s[58:59] nt
	v_add_u32_e32 v34, 0x1000, v34
	global_load_dword v47, v34, s[58:59] nt
	v_add_u32_e32 v34, 0x5000, v34
	global_load_dword v48, v34, s[58:59] nt
	v_add_u32_e32 v34, 0x1000, v34
	global_load_dword v49, v34, s[58:59] nt
	v_add_u32_e32 v34, 0x1000, v34
	global_load_dword v50, v34, s[58:59] nt
	v_add_u32_e32 v34, 0x1000, v34
	global_load_dword v51, v34, s[58:59] nt
	v_add_u32_e32 v34, 0x5000, v34
	global_load_dword v52, v34, s[58:59] nt
	v_add_u32_e32 v34, 0x1000, v34
	global_load_dword v53, v34, s[58:59] nt
	v_add_u32_e32 v34, 0x1000, v34
	global_load_dword v54, v34, s[58:59] nt
	v_add_u32_e32 v34, 0x1000, v34
	global_load_dword v55, v34, s[58:59] nt
	v_bfe_u32 v2, v0, 3, 3
	v_lshl_or_b32 v2, s6, 3, v2
	v_lshrrev_b32_e32 v3, 1, v2
	v_xor_b32_e32 v3, v3, v0
	v_lshlrev_b32_e32 v3, 4, v3
	v_and_b32_e32 v3, 0x70, v3
	v_lshl_or_b32 v6, v2, 11, v3
	v_mov_b32_e32 v7, 0
	s_lshl_b32 s9, s4, 11
	s_add_u32 s10, s54, s9
	s_addc_u32 s11, s55, 0
	s_lshl_b32 s9, s5, 11
	s_add_u32 s12, s54, 0x2940000
	s_addc_u32 s13, s55, 0
	s_add_u32 s12, s12, s9
	s_addc_u32 s13, s13, 0
	s_mov_b64 s[14:15], 0x10000
	s_mov_b64 s[16:17], 0x80
	v_lshl_add_u64 v[10:11], s[10:11], 0, v[6:7]
	v_lshl_add_u64 v[14:15], s[12:13], 0, v[6:7]
	v_lshl_add_u64 v[12:13], v[10:11], 0, s[14:15]
	v_lshl_add_u64 v[16:17], v[14:15], 0, s[14:15]
	v_bfe_u32 v20, v0, 1, 3
	v_xor_b32_e32 v22, v21, v20
	v_lshlrev_b32_e32 v24, 7, v24
	s_lshl_b32 s18, s7, 12
	s_lshl_b32 s19, s8, 12
	s_add_i32 s19, s19, 0x2000
	v_lshl_add_u32 v23, v22, 4, v24
	v_add_u32_e32 v26, s18, v23
	v_add_u32_e32 v30, s19, v23
	v_xor_b32_e32 v23, 2, v22
	v_lshl_add_u32 v23, v23, 4, v24
	v_add_u32_e32 v27, s18, v23
	v_add_u32_e32 v31, s19, v23
	v_xor_b32_e32 v23, 4, v22
	v_lshl_add_u32 v23, v23, 4, v24
	v_add_u32_e32 v28, s18, v23
	v_add_u32_e32 v32, s19, v23
	v_xor_b32_e32 v23, 6, v22
	v_lshl_add_u32 v23, v23, 4, v24
	v_add_u32_e32 v29, s18, v23
	v_add_u32_e32 v33, s19, v23
	s_add_i32 m0, s1, 0x0
	s_nop 0
	global_load_lds_dwordx4 v[10:11], off
	s_add_i32 m0, s1, 0x1000
	v_lshl_add_u64 v[10:11], v[10:11], 0, s[16:17]
	global_load_lds_dwordx4 v[12:13], off
	s_add_i32 m0, s1, 0x2000
	v_lshl_add_u64 v[12:13], v[12:13], 0, s[16:17]
	global_load_lds_dwordx4 v[14:15], off
	s_add_i32 m0, s1, 0x3000
	v_lshl_add_u64 v[14:15], v[14:15], 0, s[16:17]
	global_load_lds_dwordx4 v[16:17], off
	v_lshl_add_u64 v[16:17], v[16:17], 0, s[16:17]
	s_add_i32 m0, s1, 0x4000
	s_nop 0
	global_load_lds_dwordx4 v[10:11], off
	s_add_i32 m0, s1, 0x5000
	v_lshl_add_u64 v[10:11], v[10:11], 0, s[16:17]
	global_load_lds_dwordx4 v[12:13], off
	s_add_i32 m0, s1, 0x6000
	v_lshl_add_u64 v[12:13], v[12:13], 0, s[16:17]
	global_load_lds_dwordx4 v[14:15], off
	s_add_i32 m0, s1, 0x7000
	v_lshl_add_u64 v[14:15], v[14:15], 0, s[16:17]
	global_load_lds_dwordx4 v[16:17], off
	v_lshl_add_u64 v[16:17], v[16:17], 0, s[16:17]
	s_add_i32 m0, s1, 0x8000
	s_nop 0
	global_load_lds_dwordx4 v[10:11], off
	s_add_i32 m0, s1, 0x9000
	v_lshl_add_u64 v[10:11], v[10:11], 0, s[16:17]
	global_load_lds_dwordx4 v[12:13], off
	s_add_i32 m0, s1, 0xa000
	v_lshl_add_u64 v[12:13], v[12:13], 0, s[16:17]
	global_load_lds_dwordx4 v[14:15], off
	s_add_i32 m0, s1, 0xb000
	v_lshl_add_u64 v[14:15], v[14:15], 0, s[16:17]
	global_load_lds_dwordx4 v[16:17], off
	v_lshl_add_u64 v[16:17], v[16:17], 0, s[16:17]
	s_waitcnt vmcnt(8)
	s_barrier
; DI void gemm_out(const Params& p, char* lds) {
;     ...
;         for (int kt = 0; kt < 16; ++kt) {
;             if (kt + 1 < 16) OSTAGE((kt + 1) & 1, kt + 1);
;             const char* sb = lds + (kt & 1) * 28672; const char* sa = sb + 16384;
; #pragma unroll
;             for (int ks = 0; ks < 2; ++ks) {
;                 bf16x8 fw[4], fx[3];
; #pragma unroll
;                 for (int ct = 0; ct < 4; ++ct) fw[ct] = *(const bf16x8*)(sb + swz(wn * 64 + ct * 16 + q, 4 * ks + g));
; #pragma unroll
;                 for (int tt = 0; tt < 3; ++tt) fx[tt] = *(const bf16x8*)(sa + swz(wm * 48 + tt * 16 + q, 4 * ks + g));
; #pragma unroll
;                 for (int ct = 0; ct < 4; ++ct)
; #pragma unroll
;                     for (int tt = 0; tt < 3; ++tt) acc[ct][tt] = __builtin_amdgcn_mfma_f32_16x16x32_bf16(fw[ct], fx[tt], acc[ct][tt], 0, 0, 0);
;             }
;             __syncthreads();
;         }
	s_add_i32 m0, s1, 0xc000
	s_nop 0
	global_load_lds_dwordx4 v[10:11], off
	s_add_i32 m0, s1, 0xd000
	v_lshl_add_u64 v[10:11], v[10:11], 0, s[16:17]
	global_load_lds_dwordx4 v[12:13], off
	s_add_i32 m0, s1, 0xe000
	v_lshl_add_u64 v[12:13], v[12:13], 0, s[16:17]
	global_load_lds_dwordx4 v[14:15], off
	s_add_i32 m0, s1, 0xf000
	v_lshl_add_u64 v[14:15], v[14:15], 0, s[16:17]
	global_load_lds_dwordx4 v[16:17], off
	v_lshl_add_u64 v[16:17], v[16:17], 0, s[16:17]
	ds_read_b128 v[80:83], v26 offset:0
	ds_read_b128 v[96:99], v30 offset:0
	ds_read_b128 v[84:87], v27 offset:0
	ds_read_b128 v[100:103], v31 offset:0
	ds_read_b128 v[88:91], v28 offset:0
	ds_read_b128 v[104:107], v32 offset:0
	ds_read_b128 v[92:95], v29 offset:0
	ds_read_b128 v[108:111], v33 offset:0
	s_waitcnt lgkmcnt(6)
	v_mfma_f32_32x32x16_bf16 v[64:79], v[80:83], v[96:99], 0
	s_waitcnt lgkmcnt(4)
	v_mfma_f32_32x32x16_bf16 v[64:79], v[84:87], v[100:103], v[64:79]
	s_waitcnt lgkmcnt(2)
	v_mfma_f32_32x32x16_bf16 v[64:79], v[88:91], v[104:107], v[64:79]
	s_waitcnt lgkmcnt(0)
	v_mfma_f32_32x32x16_bf16 v[64:79], v[92:95], v[108:111], v[64:79]
	s_waitcnt vmcnt(8)
	s_barrier
	s_add_i32 m0, s1, 0x0
	s_nop 0
	global_load_lds_dwordx4 v[10:11], off
	s_add_i32 m0, s1, 0x1000
	v_lshl_add_u64 v[10:11], v[10:11], 0, s[16:17]
	global_load_lds_dwordx4 v[12:13], off
	s_add_i32 m0, s1, 0x2000
	v_lshl_add_u64 v[12:13], v[12:13], 0, s[16:17]
	global_load_lds_dwordx4 v[14:15], off
	s_add_i32 m0, s1, 0x3000
	v_lshl_add_u64 v[14:15], v[14:15], 0, s[16:17]
	global_load_lds_dwordx4 v[16:17], off
	v_lshl_add_u64 v[16:17], v[16:17], 0, s[16:17]
	ds_read_b128 v[80:83], v26 offset:16384
	ds_read_b128 v[96:99], v30 offset:16384
	ds_read_b128 v[84:87], v27 offset:16384
	ds_read_b128 v[100:103], v31 offset:16384
	ds_read_b128 v[88:91], v28 offset:16384
	ds_read_b128 v[104:107], v32 offset:16384
	ds_read_b128 v[92:95], v29 offset:16384
	ds_read_b128 v[108:111], v33 offset:16384
	s_waitcnt lgkmcnt(6)
	v_mfma_f32_32x32x16_bf16 v[64:79], v[80:83], v[96:99], v[64:79]
	s_waitcnt lgkmcnt(4)
	v_mfma_f32_32x32x16_bf16 v[64:79], v[84:87], v[100:103], v[64:79]
	s_waitcnt lgkmcnt(2)
	v_mfma_f32_32x32x16_bf16 v[64:79], v[88:91], v[104:107], v[64:79]
	s_waitcnt lgkmcnt(0)
	v_mfma_f32_32x32x16_bf16 v[64:79], v[92:95], v[108:111], v[64:79]
	s_waitcnt vmcnt(8)
	s_barrier
	s_add_i32 m0, s1, 0x4000
	s_nop 0
	global_load_lds_dwordx4 v[10:11], off
	s_add_i32 m0, s1, 0x5000
	v_lshl_add_u64 v[10:11], v[10:11], 0, s[16:17]
	global_load_lds_dwordx4 v[12:13], off
	s_add_i32 m0, s1, 0x6000
	v_lshl_add_u64 v[12:13], v[12:13], 0, s[16:17]
	global_load_lds_dwordx4 v[14:15], off
	s_add_i32 m0, s1, 0x7000
	v_lshl_add_u64 v[14:15], v[14:15], 0, s[16:17]
	global_load_lds_dwordx4 v[16:17], off
	v_lshl_add_u64 v[16:17], v[16:17], 0, s[16:17]
	ds_read_b128 v[80:83], v26 offset:32768
	ds_read_b128 v[96:99], v30 offset:32768
	ds_read_b128 v[84:87], v27 offset:32768
	ds_read_b128 v[100:103], v31 offset:32768
	ds_read_b128 v[88:91], v28 offset:32768
	ds_read_b128 v[104:107], v32 offset:32768
	ds_read_b128 v[92:95], v29 offset:32768
	ds_read_b128 v[108:111], v33 offset:32768
	s_waitcnt lgkmcnt(6)
	v_mfma_f32_32x32x16_bf16 v[64:79], v[80:83], v[96:99], v[64:79]
	s_waitcnt lgkmcnt(4)
	v_mfma_f32_32x32x16_bf16 v[64:79], v[84:87], v[100:103], v[64:79]
	s_waitcnt lgkmcnt(2)
	v_mfma_f32_32x32x16_bf16 v[64:79], v[88:91], v[104:107], v[64:79]
	s_waitcnt lgkmcnt(0)
	v_mfma_f32_32x32x16_bf16 v[64:79], v[92:95], v[108:111], v[64:79]
	s_waitcnt vmcnt(8)
	s_barrier
	s_add_i32 m0, s1, 0x8000
	s_nop 0
	global_load_lds_dwordx4 v[10:11], off
	s_add_i32 m0, s1, 0x9000
	v_lshl_add_u64 v[10:11], v[10:11], 0, s[16:17]
	global_load_lds_dwordx4 v[12:13], off
	s_add_i32 m0, s1, 0xa000
	v_lshl_add_u64 v[12:13], v[12:13], 0, s[16:17]
	global_load_lds_dwordx4 v[14:15], off
	s_add_i32 m0, s1, 0xb000
	v_lshl_add_u64 v[14:15], v[14:15], 0, s[16:17]
	global_load_lds_dwordx4 v[16:17], off
	v_lshl_add_u64 v[16:17], v[16:17], 0, s[16:17]
	ds_read_b128 v[80:83], v26 offset:49152
	ds_read_b128 v[96:99], v30 offset:49152
	ds_read_b128 v[84:87], v27 offset:49152
	ds_read_b128 v[100:103], v31 offset:49152
	ds_read_b128 v[88:91], v28 offset:49152
	ds_read_b128 v[104:107], v32 offset:49152
	ds_read_b128 v[92:95], v29 offset:49152
	ds_read_b128 v[108:111], v33 offset:49152
	s_waitcnt lgkmcnt(6)
	v_mfma_f32_32x32x16_bf16 v[64:79], v[80:83], v[96:99], v[64:79]
	s_waitcnt lgkmcnt(4)
	v_mfma_f32_32x32x16_bf16 v[64:79], v[84:87], v[100:103], v[64:79]
	s_waitcnt lgkmcnt(2)
	v_mfma_f32_32x32x16_bf16 v[64:79], v[88:91], v[104:107], v[64:79]
	s_waitcnt lgkmcnt(0)
	v_mfma_f32_32x32x16_bf16 v[64:79], v[92:95], v[108:111], v[64:79]
	s_waitcnt vmcnt(8)
	s_barrier
	s_add_i32 m0, s1, 0xc000
	s_nop 0
	global_load_lds_dwordx4 v[10:11], off
	s_add_i32 m0, s1, 0xd000
	v_lshl_add_u64 v[10:11], v[10:11], 0, s[16:17]
	global_load_lds_dwordx4 v[12:13], off
	s_add_i32 m0, s1, 0xe000
	v_lshl_add_u64 v[12:13], v[12:13], 0, s[16:17]
	global_load_lds_dwordx4 v[14:15], off
	s_add_i32 m0, s1, 0xf000
	v_lshl_add_u64 v[14:15], v[14:15], 0, s[16:17]
	global_load_lds_dwordx4 v[16:17], off
	v_lshl_add_u64 v[16:17], v[16:17], 0, s[16:17]
	ds_read_b128 v[80:83], v26 offset:0
	ds_read_b128 v[96:99], v30 offset:0
	ds_read_b128 v[84:87], v27 offset:0
	ds_read_b128 v[100:103], v31 offset:0
	ds_read_b128 v[88:91], v28 offset:0
	ds_read_b128 v[104:107], v32 offset:0
	ds_read_b128 v[92:95], v29 offset:0
	ds_read_b128 v[108:111], v33 offset:0
	s_waitcnt lgkmcnt(6)
	v_mfma_f32_32x32x16_bf16 v[64:79], v[80:83], v[96:99], v[64:79]
	s_waitcnt lgkmcnt(4)
	v_mfma_f32_32x32x16_bf16 v[64:79], v[84:87], v[100:103], v[64:79]
	s_waitcnt lgkmcnt(2)
	v_mfma_f32_32x32x16_bf16 v[64:79], v[88:91], v[104:107], v[64:79]
	s_waitcnt lgkmcnt(0)
	v_mfma_f32_32x32x16_bf16 v[64:79], v[92:95], v[108:111], v[64:79]
	s_waitcnt vmcnt(8)
	s_barrier
; DI void gemm_out(const Params& p, char* lds) {
;     ...
;         for (int kt = 0; kt < 16; ++kt) {
;             if (kt + 1 < 16) OSTAGE((kt + 1) & 1, kt + 1);
;             const char* sb = lds + (kt & 1) * 28672; const char* sa = sb + 16384;
; #pragma unroll
;             for (int ks = 0; ks < 2; ++ks) {
;                 bf16x8 fw[4], fx[3];
; #pragma unroll
;                 for (int ct = 0; ct < 4; ++ct) fw[ct] = *(const bf16x8*)(sb + swz(wn * 64 + ct * 16 + q, 4 * ks + g));
; #pragma unroll
;                 for (int tt = 0; tt < 3; ++tt) fx[tt] = *(const bf16x8*)(sa + swz(wm * 48 + tt * 16 + q, 4 * ks + g));
; #pragma unroll
;                 for (int ct = 0; ct < 4; ++ct)
; #pragma unroll
;                     for (int tt = 0; tt < 3; ++tt) acc[ct][tt] = __builtin_amdgcn_mfma_f32_16x16x32_bf16(fw[ct], fx[tt], acc[ct][tt], 0, 0, 0);
;             }
;             __syncthreads();
;         }
	s_add_i32 m0, s1, 0x0
	s_nop 0
	global_load_lds_dwordx4 v[10:11], off
	s_add_i32 m0, s1, 0x1000
	v_lshl_add_u64 v[10:11], v[10:11], 0, s[16:17]
	global_load_lds_dwordx4 v[12:13], off
	s_add_i32 m0, s1, 0x2000
	v_lshl_add_u64 v[12:13], v[12:13], 0, s[16:17]
	global_load_lds_dwordx4 v[14:15], off
	s_add_i32 m0, s1, 0x3000
	v_lshl_add_u64 v[14:15], v[14:15], 0, s[16:17]
	global_load_lds_dwordx4 v[16:17], off
	v_lshl_add_u64 v[16:17], v[16:17], 0, s[16:17]
	ds_read_b128 v[80:83], v26 offset:16384
	ds_read_b128 v[96:99], v30 offset:16384
	ds_read_b128 v[84:87], v27 offset:16384
	ds_read_b128 v[100:103], v31 offset:16384
	ds_read_b128 v[88:91], v28 offset:16384
	ds_read_b128 v[104:107], v32 offset:16384
	ds_read_b128 v[92:95], v29 offset:16384
	ds_read_b128 v[108:111], v33 offset:16384
	s_waitcnt lgkmcnt(6)
	v_mfma_f32_32x32x16_bf16 v[64:79], v[80:83], v[96:99], v[64:79]
	s_waitcnt lgkmcnt(4)
	v_mfma_f32_32x32x16_bf16 v[64:79], v[84:87], v[100:103], v[64:79]
	s_waitcnt lgkmcnt(2)
	v_mfma_f32_32x32x16_bf16 v[64:79], v[88:91], v[104:107], v[64:79]
	s_waitcnt lgkmcnt(0)
	v_mfma_f32_32x32x16_bf16 v[64:79], v[92:95], v[108:111], v[64:79]
	s_waitcnt vmcnt(8)
	s_barrier
	s_add_i32 m0, s1, 0x4000
	s_nop 0
	global_load_lds_dwordx4 v[10:11], off
	s_add_i32 m0, s1, 0x5000
	v_lshl_add_u64 v[10:11], v[10:11], 0, s[16:17]
	global_load_lds_dwordx4 v[12:13], off
	s_add_i32 m0, s1, 0x6000
	v_lshl_add_u64 v[12:13], v[12:13], 0, s[16:17]
	global_load_lds_dwordx4 v[14:15], off
	s_add_i32 m0, s1, 0x7000
	v_lshl_add_u64 v[14:15], v[14:15], 0, s[16:17]
	global_load_lds_dwordx4 v[16:17], off
	v_lshl_add_u64 v[16:17], v[16:17], 0, s[16:17]
	ds_read_b128 v[80:83], v26 offset:32768
	ds_read_b128 v[96:99], v30 offset:32768
	ds_read_b128 v[84:87], v27 offset:32768
	ds_read_b128 v[100:103], v31 offset:32768
	ds_read_b128 v[88:91], v28 offset:32768
	ds_read_b128 v[104:107], v32 offset:32768
	ds_read_b128 v[92:95], v29 offset:32768
	ds_read_b128 v[108:111], v33 offset:32768
	s_waitcnt lgkmcnt(6)
	v_mfma_f32_32x32x16_bf16 v[64:79], v[80:83], v[96:99], v[64:79]
	s_waitcnt lgkmcnt(4)
	v_mfma_f32_32x32x16_bf16 v[64:79], v[84:87], v[100:103], v[64:79]
	s_waitcnt lgkmcnt(2)
	v_mfma_f32_32x32x16_bf16 v[64:79], v[88:91], v[104:107], v[64:79]
	s_waitcnt lgkmcnt(0)
	v_mfma_f32_32x32x16_bf16 v[64:79], v[92:95], v[108:111], v[64:79]
	s_waitcnt vmcnt(8)
	s_barrier
	s_add_i32 m0, s1, 0x8000
	s_nop 0
	global_load_lds_dwordx4 v[10:11], off
	s_add_i32 m0, s1, 0x9000
	v_lshl_add_u64 v[10:11], v[10:11], 0, s[16:17]
	global_load_lds_dwordx4 v[12:13], off
	s_add_i32 m0, s1, 0xa000
	v_lshl_add_u64 v[12:13], v[12:13], 0, s[16:17]
	global_load_lds_dwordx4 v[14:15], off
	s_add_i32 m0, s1, 0xb000
	v_lshl_add_u64 v[14:15], v[14:15], 0, s[16:17]
	global_load_lds_dwordx4 v[16:17], off
	v_lshl_add_u64 v[16:17], v[16:17], 0, s[16:17]
	ds_read_b128 v[80:83], v26 offset:49152
	ds_read_b128 v[96:99], v30 offset:49152
	ds_read_b128 v[84:87], v27 offset:49152
	ds_read_b128 v[100:103], v31 offset:49152
	ds_read_b128 v[88:91], v28 offset:49152
	ds_read_b128 v[104:107], v32 offset:49152
	ds_read_b128 v[92:95], v29 offset:49152
	ds_read_b128 v[108:111], v33 offset:49152
	s_waitcnt lgkmcnt(6)
	v_mfma_f32_32x32x16_bf16 v[64:79], v[80:83], v[96:99], v[64:79]
	s_waitcnt lgkmcnt(4)
	v_mfma_f32_32x32x16_bf16 v[64:79], v[84:87], v[100:103], v[64:79]
	s_waitcnt lgkmcnt(2)
	v_mfma_f32_32x32x16_bf16 v[64:79], v[88:91], v[104:107], v[64:79]
	s_waitcnt lgkmcnt(0)
	v_mfma_f32_32x32x16_bf16 v[64:79], v[92:95], v[108:111], v[64:79]
	s_waitcnt vmcnt(8)
	s_barrier
	s_add_i32 m0, s1, 0xc000
	s_nop 0
	global_load_lds_dwordx4 v[10:11], off
	s_add_i32 m0, s1, 0xd000
	v_lshl_add_u64 v[10:11], v[10:11], 0, s[16:17]
	global_load_lds_dwordx4 v[12:13], off
	s_add_i32 m0, s1, 0xe000
	v_lshl_add_u64 v[12:13], v[12:13], 0, s[16:17]
	global_load_lds_dwordx4 v[14:15], off
	s_add_i32 m0, s1, 0xf000
	v_lshl_add_u64 v[14:15], v[14:15], 0, s[16:17]
	global_load_lds_dwordx4 v[16:17], off
	v_lshl_add_u64 v[16:17], v[16:17], 0, s[16:17]
	ds_read_b128 v[80:83], v26 offset:0
	ds_read_b128 v[96:99], v30 offset:0
	ds_read_b128 v[84:87], v27 offset:0
	ds_read_b128 v[100:103], v31 offset:0
	ds_read_b128 v[88:91], v28 offset:0
	ds_read_b128 v[104:107], v32 offset:0
	ds_read_b128 v[92:95], v29 offset:0
	ds_read_b128 v[108:111], v33 offset:0
	s_waitcnt lgkmcnt(6)
	v_mfma_f32_32x32x16_bf16 v[64:79], v[80:83], v[96:99], v[64:79]
	s_waitcnt lgkmcnt(4)
	v_mfma_f32_32x32x16_bf16 v[64:79], v[84:87], v[100:103], v[64:79]
	s_waitcnt lgkmcnt(2)
	v_mfma_f32_32x32x16_bf16 v[64:79], v[88:91], v[104:107], v[64:79]
	s_waitcnt lgkmcnt(0)
	v_mfma_f32_32x32x16_bf16 v[64:79], v[92:95], v[108:111], v[64:79]
	s_waitcnt vmcnt(8)
	s_barrier
	s_add_i32 m0, s1, 0x0
	s_nop 0
	global_load_lds_dwordx4 v[10:11], off
	s_add_i32 m0, s1, 0x1000
	v_lshl_add_u64 v[10:11], v[10:11], 0, s[16:17]
	global_load_lds_dwordx4 v[12:13], off
	s_add_i32 m0, s1, 0x2000
	v_lshl_add_u64 v[12:13], v[12:13], 0, s[16:17]
	global_load_lds_dwordx4 v[14:15], off
	s_add_i32 m0, s1, 0x3000
	v_lshl_add_u64 v[14:15], v[14:15], 0, s[16:17]
	global_load_lds_dwordx4 v[16:17], off
	v_lshl_add_u64 v[16:17], v[16:17], 0, s[16:17]
	ds_read_b128 v[80:83], v26 offset:16384
	ds_read_b128 v[96:99], v30 offset:16384
	ds_read_b128 v[84:87], v27 offset:16384
	ds_read_b128 v[100:103], v31 offset:16384
	ds_read_b128 v[88:91], v28 offset:16384
	ds_read_b128 v[104:107], v32 offset:16384
	ds_read_b128 v[92:95], v29 offset:16384
	ds_read_b128 v[108:111], v33 offset:16384
	s_waitcnt lgkmcnt(6)
	v_mfma_f32_32x32x16_bf16 v[64:79], v[80:83], v[96:99], v[64:79]
	s_waitcnt lgkmcnt(4)
	v_mfma_f32_32x32x16_bf16 v[64:79], v[84:87], v[100:103], v[64:79]
	s_waitcnt lgkmcnt(2)
	v_mfma_f32_32x32x16_bf16 v[64:79], v[88:91], v[104:107], v[64:79]
	s_waitcnt lgkmcnt(0)
	v_mfma_f32_32x32x16_bf16 v[64:79], v[92:95], v[108:111], v[64:79]
	s_waitcnt vmcnt(8)
	s_barrier
; DI void gemm_out(const Params& p, char* lds) {
;     ...
;         for (int kt = 0; kt < 16; ++kt) {
;             if (kt + 1 < 16) OSTAGE((kt + 1) & 1, kt + 1);
;             const char* sb = lds + (kt & 1) * 28672; const char* sa = sb + 16384;
; #pragma unroll
;             for (int ks = 0; ks < 2; ++ks) {
;                 bf16x8 fw[4], fx[3];
; #pragma unroll
;                 for (int ct = 0; ct < 4; ++ct) fw[ct] = *(const bf16x8*)(sb + swz(wn * 64 + ct * 16 + q, 4 * ks + g));
; #pragma unroll
;                 for (int tt = 0; tt < 3; ++tt) fx[tt] = *(const bf16x8*)(sa + swz(wm * 48 + tt * 16 + q, 4 * ks + g));
; #pragma unroll
;                 for (int ct = 0; ct < 4; ++ct)
; #pragma unroll
;                     for (int tt = 0; tt < 3; ++tt) acc[ct][tt] = __builtin_amdgcn_mfma_f32_16x16x32_bf16(fw[ct], fx[tt], acc[ct][tt], 0, 0, 0);
;             }
;             __syncthreads();
;         }
	s_add_i32 m0, s1, 0x4000
	s_nop 0
	global_load_lds_dwordx4 v[10:11], off
	s_add_i32 m0, s1, 0x5000
	v_lshl_add_u64 v[10:11], v[10:11], 0, s[16:17]
	global_load_lds_dwordx4 v[12:13], off
	s_add_i32 m0, s1, 0x6000
	v_lshl_add_u64 v[12:13], v[12:13], 0, s[16:17]
	global_load_lds_dwordx4 v[14:15], off
	s_add_i32 m0, s1, 0x7000
	v_lshl_add_u64 v[14:15], v[14:15], 0, s[16:17]
	global_load_lds_dwordx4 v[16:17], off
	v_lshl_add_u64 v[16:17], v[16:17], 0, s[16:17]
	ds_read_b128 v[80:83], v26 offset:32768
	ds_read_b128 v[96:99], v30 offset:32768
	ds_read_b128 v[84:87], v27 offset:32768
	ds_read_b128 v[100:103], v31 offset:32768
	ds_read_b128 v[88:91], v28 offset:32768
	ds_read_b128 v[104:107], v32 offset:32768
	ds_read_b128 v[92:95], v29 offset:32768
	ds_read_b128 v[108:111], v33 offset:32768
	s_waitcnt lgkmcnt(6)
	v_mfma_f32_32x32x16_bf16 v[64:79], v[80:83], v[96:99], v[64:79]
	s_waitcnt lgkmcnt(4)
	v_mfma_f32_32x32x16_bf16 v[64:79], v[84:87], v[100:103], v[64:79]
	s_waitcnt lgkmcnt(2)
	v_mfma_f32_32x32x16_bf16 v[64:79], v[88:91], v[104:107], v[64:79]
	s_waitcnt lgkmcnt(0)
	v_mfma_f32_32x32x16_bf16 v[64:79], v[92:95], v[108:111], v[64:79]
	s_waitcnt vmcnt(8)
	s_barrier
	s_add_i32 m0, s1, 0x8000
	s_nop 0
	global_load_lds_dwordx4 v[10:11], off
	s_add_i32 m0, s1, 0x9000
	v_lshl_add_u64 v[10:11], v[10:11], 0, s[16:17]
	global_load_lds_dwordx4 v[12:13], off
	s_add_i32 m0, s1, 0xa000
	v_lshl_add_u64 v[12:13], v[12:13], 0, s[16:17]
	global_load_lds_dwordx4 v[14:15], off
	s_add_i32 m0, s1, 0xb000
	v_lshl_add_u64 v[14:15], v[14:15], 0, s[16:17]
	global_load_lds_dwordx4 v[16:17], off
	v_lshl_add_u64 v[16:17], v[16:17], 0, s[16:17]
	ds_read_b128 v[80:83], v26 offset:49152
	ds_read_b128 v[96:99], v30 offset:49152
	ds_read_b128 v[84:87], v27 offset:49152
	ds_read_b128 v[100:103], v31 offset:49152
	ds_read_b128 v[88:91], v28 offset:49152
	ds_read_b128 v[104:107], v32 offset:49152
	ds_read_b128 v[92:95], v29 offset:49152
	ds_read_b128 v[108:111], v33 offset:49152
	s_waitcnt lgkmcnt(6)
	v_mfma_f32_32x32x16_bf16 v[64:79], v[80:83], v[96:99], v[64:79]
	s_waitcnt lgkmcnt(4)
	v_mfma_f32_32x32x16_bf16 v[64:79], v[84:87], v[100:103], v[64:79]
	s_waitcnt lgkmcnt(2)
	v_mfma_f32_32x32x16_bf16 v[64:79], v[88:91], v[104:107], v[64:79]
	s_waitcnt lgkmcnt(0)
	v_mfma_f32_32x32x16_bf16 v[64:79], v[92:95], v[108:111], v[64:79]
	s_waitcnt vmcnt(8)
	s_barrier
	s_add_i32 m0, s1, 0xc000
	s_nop 0
	global_load_lds_dwordx4 v[10:11], off
	s_add_i32 m0, s1, 0xd000
	v_lshl_add_u64 v[10:11], v[10:11], 0, s[16:17]
	global_load_lds_dwordx4 v[12:13], off
	s_add_i32 m0, s1, 0xe000
	v_lshl_add_u64 v[12:13], v[12:13], 0, s[16:17]
	global_load_lds_dwordx4 v[14:15], off
	s_add_i32 m0, s1, 0xf000
	v_lshl_add_u64 v[14:15], v[14:15], 0, s[16:17]
	global_load_lds_dwordx4 v[16:17], off
	v_lshl_add_u64 v[16:17], v[16:17], 0, s[16:17]
	ds_read_b128 v[80:83], v26 offset:0
	ds_read_b128 v[96:99], v30 offset:0
	ds_read_b128 v[84:87], v27 offset:0
	ds_read_b128 v[100:103], v31 offset:0
	ds_read_b128 v[88:91], v28 offset:0
	ds_read_b128 v[104:107], v32 offset:0
	ds_read_b128 v[92:95], v29 offset:0
	ds_read_b128 v[108:111], v33 offset:0
	s_waitcnt lgkmcnt(6)
	v_mfma_f32_32x32x16_bf16 v[64:79], v[80:83], v[96:99], v[64:79]
	s_waitcnt lgkmcnt(4)
	v_mfma_f32_32x32x16_bf16 v[64:79], v[84:87], v[100:103], v[64:79]
	s_waitcnt lgkmcnt(2)
	v_mfma_f32_32x32x16_bf16 v[64:79], v[88:91], v[104:107], v[64:79]
	s_waitcnt lgkmcnt(0)
	v_mfma_f32_32x32x16_bf16 v[64:79], v[92:95], v[108:111], v[64:79]
	s_waitcnt vmcnt(8)
	s_barrier
; DI void gemm_out(const Params& p, char* lds) {
;     ...
;         for (int kt = 0; kt < 16; ++kt) {
;             if (kt + 1 < 16) OSTAGE((kt + 1) & 1, kt + 1);
;             const char* sb = lds + (kt & 1) * 28672; const char* sa = sb + 16384;
; #pragma unroll
;             for (int ks = 0; ks < 2; ++ks) {
;                 bf16x8 fw[4], fx[3];
; #pragma unroll
;                 for (int ct = 0; ct < 4; ++ct) fw[ct] = *(const bf16x8*)(sb + swz(wn * 64 + ct * 16 + q, 4 * ks + g));
; #pragma unroll
;                 for (int tt = 0; tt < 3; ++tt) fx[tt] = *(const bf16x8*)(sa + swz(wm * 48 + tt * 16 + q, 4 * ks + g));
; #pragma unroll
;                 for (int ct = 0; ct < 4; ++ct)
; #pragma unroll
;                     for (int tt = 0; tt < 3; ++tt) acc[ct][tt] = __builtin_amdgcn_mfma_f32_16x16x32_bf16(fw[ct], fx[tt], acc[ct][tt], 0, 0, 0);
;             }
;             __syncthreads();
;         }
;     ...
; #pragma unroll
;         for (int tt = 0; tt < 3; ++tt) {
;             const int row = m0 + wm * 48 + tt * 16 + q;
;             const float* xr = row < NTP ? p.x_p + (size_t)row * DM : p.x_s + (size_t)(row - NTP) * DM;
;             float* o = p.out + (size_t)row * DM;
; #pragma unroll
;             for (int ct = 0; ct < 4; ++ct) { const int col = n0 + wn * 64 + ct * 16 + 4 * g; const float4 xv = xres[tt][ct];
;                 const f32x4 w = {xv.x + acc[ct][tt][0], xv.y + acc[ct][tt][1], xv.z + acc[ct][tt][2], xv.w + acc[ct][tt][3]}; __builtin_nontemporal_store(w, (f32x4*)(o + col)); }
	ds_read_b128 v[80:83], v26 offset:16384
	ds_read_b128 v[96:99], v30 offset:16384
	ds_read_b128 v[84:87], v27 offset:16384
	ds_read_b128 v[100:103], v31 offset:16384
	ds_read_b128 v[88:91], v28 offset:16384
	ds_read_b128 v[104:107], v32 offset:16384
	ds_read_b128 v[92:95], v29 offset:16384
	ds_read_b128 v[108:111], v33 offset:16384
	s_waitcnt lgkmcnt(6)
	v_mfma_f32_32x32x16_bf16 v[64:79], v[80:83], v[96:99], v[64:79]
	s_waitcnt lgkmcnt(4)
	v_mfma_f32_32x32x16_bf16 v[64:79], v[84:87], v[100:103], v[64:79]
	s_waitcnt lgkmcnt(2)
	v_mfma_f32_32x32x16_bf16 v[64:79], v[88:91], v[104:107], v[64:79]
	s_waitcnt lgkmcnt(0)
	v_mfma_f32_32x32x16_bf16 v[64:79], v[92:95], v[108:111], v[64:79]
	s_waitcnt vmcnt(4)
	s_barrier
	ds_read_b128 v[80:83], v26 offset:32768
	ds_read_b128 v[96:99], v30 offset:32768
	ds_read_b128 v[84:87], v27 offset:32768
	ds_read_b128 v[100:103], v31 offset:32768
	ds_read_b128 v[88:91], v28 offset:32768
	ds_read_b128 v[104:107], v32 offset:32768
	ds_read_b128 v[92:95], v29 offset:32768
	ds_read_b128 v[108:111], v33 offset:32768
	s_waitcnt lgkmcnt(6)
	v_mfma_f32_32x32x16_bf16 v[64:79], v[80:83], v[96:99], v[64:79]
	s_waitcnt lgkmcnt(4)
	v_mfma_f32_32x32x16_bf16 v[64:79], v[84:87], v[100:103], v[64:79]
	s_waitcnt lgkmcnt(2)
	v_mfma_f32_32x32x16_bf16 v[64:79], v[88:91], v[104:107], v[64:79]
	s_waitcnt lgkmcnt(0)
	v_mfma_f32_32x32x16_bf16 v[64:79], v[92:95], v[108:111], v[64:79]
	s_waitcnt vmcnt(0)
	s_barrier
	ds_read_b128 v[80:83], v26 offset:49152
	ds_read_b128 v[96:99], v30 offset:49152
	ds_read_b128 v[84:87], v27 offset:49152
	ds_read_b128 v[100:103], v31 offset:49152
	ds_read_b128 v[88:91], v28 offset:49152
	ds_read_b128 v[104:107], v32 offset:49152
	ds_read_b128 v[92:95], v29 offset:49152
	ds_read_b128 v[108:111], v33 offset:49152
	s_waitcnt lgkmcnt(6)
	v_mfma_f32_32x32x16_bf16 v[64:79], v[80:83], v[96:99], v[64:79]
	s_waitcnt lgkmcnt(4)
	v_mfma_f32_32x32x16_bf16 v[64:79], v[84:87], v[100:103], v[64:79]
	s_waitcnt lgkmcnt(2)
	v_mfma_f32_32x32x16_bf16 v[64:79], v[88:91], v[104:107], v[64:79]
	s_waitcnt lgkmcnt(0)
	v_mfma_f32_32x32x16_bf16 v[64:79], v[92:95], v[108:111], v[64:79]
	s_nop 15
	s_nop 7
	v_add_f32_e32 v64, v64, v40
	global_store_dword v35, v64, s[52:53] nt
	v_add_u32_e32 v35, 0x1000, v35
	v_add_f32_e32 v65, v65, v41
	global_store_dword v35, v65, s[52:53] nt
	v_add_u32_e32 v35, 0x1000, v35
	v_add_f32_e32 v66, v66, v42
	global_store_dword v35, v66, s[52:53] nt
	v_add_u32_e32 v35, 0x1000, v35
	v_add_f32_e32 v67, v67, v43
	global_store_dword v35, v67, s[52:53] nt
	v_add_u32_e32 v35, 0x5000, v35
	v_add_f32_e32 v68, v68, v44
	global_store_dword v35, v68, s[52:53] nt
	v_add_u32_e32 v35, 0x1000, v35
	v_add_f32_e32 v69, v69, v45
	global_store_dword v35, v69, s[52:53] nt
	v_add_u32_e32 v35, 0x1000, v35
	v_add_f32_e32 v70, v70, v46
	global_store_dword v35, v70, s[52:53] nt
	v_add_u32_e32 v35, 0x1000, v35
	v_add_f32_e32 v71, v71, v47
	global_store_dword v35, v71, s[52:53] nt
	v_add_u32_e32 v35, 0x5000, v35
	v_add_f32_e32 v72, v72, v48
	global_store_dword v35, v72, s[52:53] nt
	v_add_u32_e32 v35, 0x1000, v35
	v_add_f32_e32 v73, v73, v49
	global_store_dword v35, v73, s[52:53] nt
	v_add_u32_e32 v35, 0x1000, v35
	v_add_f32_e32 v74, v74, v50
	global_store_dword v35, v74, s[52:53] nt
	v_add_u32_e32 v35, 0x1000, v35
	v_add_f32_e32 v75, v75, v51
	global_store_dword v35, v75, s[52:53] nt
	v_add_u32_e32 v35, 0x5000, v35
	v_add_f32_e32 v76, v76, v52
	global_store_dword v35, v76, s[52:53] nt
	v_add_u32_e32 v35, 0x1000, v35
	v_add_f32_e32 v77, v77, v53
	global_store_dword v35, v77, s[52:53] nt
	v_add_u32_e32 v35, 0x1000, v35
	v_add_f32_e32 v78, v78, v54
	global_store_dword v35, v78, s[52:53] nt
	v_add_u32_e32 v35, 0x1000, v35
	v_add_f32_e32 v79, v79, v55
	global_store_dword v35, v79, s[52:53] nt
